# peeled first K-iteration: first load segment no longer waits for the previous unit's epilogue stores (nothing older is needed there)
# speedup vs baseline: 1.0027x; 1.0000x over previous
.LBB0_36:
	s_add_u32 s34, s28, 0x100
	s_addc_u32 s35, s29, 0
	s_mov_b32 s79, -2
	s_waitcnt lgkmcnt(0)
	s_add_u32 s10, s24, 0x100
	s_addc_u32 s11, s25, 0
	s_add_i32 s0, 0, 0x10000
	s_cmpk_eq_i32 s79, 0x54
	s_cselect_b32 s31, s21, s11
	s_cselect_b32 s30, s20, s10
	s_cselect_b32 s29, s23, s35
	s_cselect_b32 s28, s22, s34
	s_add_i32 s59, 0, 0x14000
	v_add_u32_e32 v140, s0, v251
	v_add_u32_e32 v156, s59, v251
	ds_read_b128 v[124:127], v140
	ds_read_b128 v[128:131], v140 offset:1024
	ds_read_b128 v[132:135], v140 offset:2048
	ds_read_b128 v[140:143], v140 offset:3072
	ds_read_b128 v[144:147], v156
	ds_read_b128 v[148:151], v156 offset:1024
	ds_read_b128 v[152:155], v156 offset:2048
	ds_read_b128 v[156:159], v156 offset:3072
	v_lshl_add_u64 v[192:193], s[24:25], 0, v[214:215]
	s_add_i32 m0, s41, 0xc000
	ds_read_b128 v[160:163], v253
	ds_read_b128 v[164:167], v253 offset:1024
	ds_read_b128 v[168:171], v253 offset:2048
	ds_read_b128 v[172:175], v253 offset:3072
	ds_read_b128 v[176:179], v253 offset:4096
	ds_read_b128 v[180:183], v253 offset:5120
	ds_read_b128 v[184:187], v253 offset:6144
	ds_read_b128 v[188:191], v253 offset:7168
	global_load_lds_dwordx4 v[192:193], off
	v_lshl_add_u64 v[192:193], s[24:25], 0, v[216:217]
	s_add_i32 m0, s41, 0xe000
	s_nop 0
	global_load_lds_dwordx4 v[192:193], off
	s_waitcnt vmcnt(63)
	s_waitcnt lgkmcnt(0)
	s_barrier
	s_setprio 1
	s_waitcnt lgkmcnt(0)
	v_mfma_f32_16x16x32_bf16 v[136:139], v[124:127], v[160:163], 0
	v_mfma_f32_16x16x32_bf16 v[120:123], v[132:135], v[160:163], 0
	v_mfma_f32_16x16x32_bf16 v[116:119], v[124:127], v[168:171], 0
	v_mfma_f32_16x16x32_bf16 v[104:107], v[132:135], v[168:171], 0
	v_mfma_f32_16x16x32_bf16 v[100:103], v[124:127], v[176:179], 0
	v_mfma_f32_16x16x32_bf16 v[88:91], v[132:135], v[176:179], 0
	v_mfma_f32_16x16x32_bf16 v[84:87], v[124:127], v[184:187], 0
	v_mfma_f32_16x16x32_bf16 v[72:75], v[132:135], v[184:187], 0
	v_mfma_f32_16x16x32_bf16 v[136:139], v[128:131], v[164:167], v[136:139]
	v_mfma_f32_16x16x32_bf16 v[120:123], v[140:143], v[164:167], v[120:123]
	v_mfma_f32_16x16x32_bf16 v[116:119], v[128:131], v[172:175], v[116:119]
	v_mfma_f32_16x16x32_bf16 v[104:107], v[140:143], v[172:175], v[104:107]
	v_mfma_f32_16x16x32_bf16 v[100:103], v[128:131], v[180:183], v[100:103]
	v_mfma_f32_16x16x32_bf16 v[88:91], v[140:143], v[180:183], v[88:91]
	v_mfma_f32_16x16x32_bf16 v[84:87], v[128:131], v[188:191], v[84:87]
	v_mfma_f32_16x16x32_bf16 v[72:75], v[140:143], v[188:191], v[72:75]
	s_setprio 0
	s_setprio 1
	v_mfma_f32_16x16x32_bf16 v[112:115], v[144:147], v[160:163], 0
	v_mfma_f32_16x16x32_bf16 v[108:111], v[152:155], v[160:163], 0
	v_mfma_f32_16x16x32_bf16 v[96:99], v[144:147], v[168:171], 0
	v_mfma_f32_16x16x32_bf16 v[92:95], v[152:155], v[168:171], 0
	v_mfma_f32_16x16x32_bf16 v[80:83], v[144:147], v[176:179], 0
	v_mfma_f32_16x16x32_bf16 v[76:79], v[152:155], v[176:179], 0
	v_mfma_f32_16x16x32_bf16 v[68:71], v[144:147], v[184:187], 0
	v_mfma_f32_16x16x32_bf16 v[64:67], v[152:155], v[184:187], 0
	v_mfma_f32_16x16x32_bf16 v[112:115], v[148:151], v[164:167], v[112:115]
	v_mfma_f32_16x16x32_bf16 v[108:111], v[156:159], v[164:167], v[108:111]
	v_mfma_f32_16x16x32_bf16 v[96:99], v[148:151], v[172:175], v[96:99]
	v_mfma_f32_16x16x32_bf16 v[92:95], v[156:159], v[172:175], v[92:95]
	v_mfma_f32_16x16x32_bf16 v[80:83], v[148:151], v[180:183], v[80:83]
	v_mfma_f32_16x16x32_bf16 v[76:79], v[156:159], v[180:183], v[76:79]
	v_mfma_f32_16x16x32_bf16 v[68:71], v[148:151], v[188:191], v[68:71]
	v_mfma_f32_16x16x32_bf16 v[64:67], v[156:159], v[188:191], v[64:67]
	s_setprio 0
	s_barrier
	s_add_i32 s0, s0, s40
	v_lshl_add_u64 v[192:193], s[28:29], 0, v[198:199]
	s_mov_b32 m0, s0
	ds_read_b128 v[160:163], v253 offset:16384
	ds_read_b128 v[164:167], v253 offset:17408
	ds_read_b128 v[168:171], v253 offset:18432
	ds_read_b128 v[172:175], v253 offset:19456
	ds_read_b128 v[176:179], v253 offset:20480
	ds_read_b128 v[180:183], v253 offset:21504
	ds_read_b128 v[184:187], v253 offset:22528
	ds_read_b128 v[188:191], v253 offset:23552
	global_load_lds_dwordx4 v[192:193], off
	s_add_i32 m0, s0, 0x2000
	s_add_u32 s0, s28, 0x160000
	v_lshl_add_u64 v[194:195], s[28:29], 0, v[212:213]
	s_addc_u32 s1, s29, 0
	s_add_i32 s24, s59, s40
	global_load_lds_dwordx4 v[194:195], off
	v_lshl_add_u64 v[196:197], s[0:1], 0, v[198:199]
	s_mov_b32 m0, s24
	v_lshl_add_u64 v[218:219], s[30:31], 0, v[212:213]
	global_load_lds_dwordx4 v[196:197], off
	v_lshl_add_u64 v[196:197], s[0:1], 0, v[212:213]
	s_add_i32 m0, s24, 0x2000
	s_nop 0
	global_load_lds_dwordx4 v[196:197], off
	v_lshl_add_u64 v[196:197], s[30:31], 0, v[198:199]
	s_mov_b32 m0, s41
	s_nop 0
	global_load_lds_dwordx4 v[196:197], off
	s_mov_b32 m0, s42
	s_nop 0
	global_load_lds_dwordx4 v[218:219], off
	s_waitcnt vmcnt(8)
	s_waitcnt lgkmcnt(0)
	s_barrier
	s_setprio 1
	s_waitcnt lgkmcnt(0)
	v_mfma_f32_16x16x32_bf16 v[60:63], v[124:127], v[160:163], 0
	v_mfma_f32_16x16x32_bf16 v[56:59], v[132:135], v[160:163], 0
	v_mfma_f32_16x16x32_bf16 v[52:55], v[124:127], v[168:171], 0
	v_mfma_f32_16x16x32_bf16 v[40:43], v[132:135], v[168:171], 0
	v_mfma_f32_16x16x32_bf16 v[36:39], v[124:127], v[176:179], 0
	v_mfma_f32_16x16x32_bf16 v[24:27], v[132:135], v[176:179], 0
	v_mfma_f32_16x16x32_bf16 v[20:23], v[124:127], v[184:187], 0
	v_mfma_f32_16x16x32_bf16 v[8:11], v[132:135], v[184:187], 0
	v_mfma_f32_16x16x32_bf16 v[60:63], v[128:131], v[164:167], v[60:63]
	v_mfma_f32_16x16x32_bf16 v[56:59], v[140:143], v[164:167], v[56:59]
	v_mfma_f32_16x16x32_bf16 v[52:55], v[128:131], v[172:175], v[52:55]
	v_mfma_f32_16x16x32_bf16 v[40:43], v[140:143], v[172:175], v[40:43]
	v_mfma_f32_16x16x32_bf16 v[36:39], v[128:131], v[180:183], v[36:39]
	v_mfma_f32_16x16x32_bf16 v[24:27], v[140:143], v[180:183], v[24:27]
	v_mfma_f32_16x16x32_bf16 v[20:23], v[128:131], v[188:191], v[20:23]
	v_mfma_f32_16x16x32_bf16 v[8:11], v[140:143], v[188:191], v[8:11]
	s_setprio 0
	s_setprio 1
	v_mfma_f32_16x16x32_bf16 v[48:51], v[144:147], v[160:163], 0
	v_mfma_f32_16x16x32_bf16 v[44:47], v[152:155], v[160:163], 0
	v_mfma_f32_16x16x32_bf16 v[32:35], v[144:147], v[168:171], 0
	v_mfma_f32_16x16x32_bf16 v[28:31], v[152:155], v[168:171], 0
	v_mfma_f32_16x16x32_bf16 v[16:19], v[144:147], v[176:179], 0
	v_mfma_f32_16x16x32_bf16 v[12:15], v[152:155], v[176:179], 0
	v_mfma_f32_16x16x32_bf16 v[4:7], v[144:147], v[184:187], 0
	v_mfma_f32_16x16x32_bf16 v[0:3], v[152:155], v[184:187], 0
	v_mfma_f32_16x16x32_bf16 v[48:51], v[148:151], v[164:167], v[48:51]
	v_mfma_f32_16x16x32_bf16 v[44:47], v[156:159], v[164:167], v[44:47]
	v_mfma_f32_16x16x32_bf16 v[32:35], v[148:151], v[172:175], v[32:35]
	v_mfma_f32_16x16x32_bf16 v[28:31], v[156:159], v[172:175], v[28:31]
	v_mfma_f32_16x16x32_bf16 v[16:19], v[148:151], v[180:183], v[16:19]
	v_mfma_f32_16x16x32_bf16 v[12:15], v[156:159], v[180:183], v[12:15]
	v_mfma_f32_16x16x32_bf16 v[4:7], v[148:151], v[188:191], v[4:7]
	v_mfma_f32_16x16x32_bf16 v[0:3], v[156:159], v[188:191], v[0:3]
	s_setprio 0
	s_barrier
	s_add_i32 s24, 0, 0x18000
	s_add_i32 s25, 0, 0x1c000
	v_add_u32_e32 v140, s24, v251
	v_add_u32_e32 v156, s25, v251
	ds_read_b128 v[124:127], v140
	ds_read_b128 v[128:131], v140 offset:1024
	ds_read_b128 v[132:135], v140 offset:2048
	ds_read_b128 v[140:143], v140 offset:3072
	ds_read_b128 v[144:147], v156
	ds_read_b128 v[148:151], v156 offset:1024
	ds_read_b128 v[152:155], v156 offset:2048
	ds_read_b128 v[156:159], v156 offset:3072
	s_add_u32 s0, s30, 0x160000
	s_addc_u32 s1, s31, 0
	s_mov_b32 m0, s43
	v_lshl_add_u64 v[220:221], s[0:1], 0, v[198:199]
	ds_read_b128 v[160:163], v253 offset:32768
	ds_read_b128 v[164:167], v253 offset:33792
	ds_read_b128 v[168:171], v253 offset:34816
	ds_read_b128 v[172:175], v253 offset:35840
	ds_read_b128 v[176:179], v253 offset:36864
	ds_read_b128 v[180:183], v253 offset:37888
	ds_read_b128 v[184:187], v253 offset:38912
	ds_read_b128 v[188:191], v253 offset:39936
	global_load_lds_dwordx4 v[220:221], off
	v_lshl_add_u64 v[220:221], s[0:1], 0, v[212:213]
	s_mov_b32 m0, s46
	s_nop 0
	global_load_lds_dwordx4 v[220:221], off
	s_waitcnt vmcnt(8)
	s_waitcnt lgkmcnt(0)
	s_barrier
	s_setprio 1
	s_waitcnt lgkmcnt(0)
	v_mfma_f32_16x16x32_bf16 v[136:139], v[124:127], v[160:163], v[136:139]
	v_mfma_f32_16x16x32_bf16 v[120:123], v[132:135], v[160:163], v[120:123]
	v_mfma_f32_16x16x32_bf16 v[116:119], v[124:127], v[168:171], v[116:119]
	v_mfma_f32_16x16x32_bf16 v[104:107], v[132:135], v[168:171], v[104:107]
	v_mfma_f32_16x16x32_bf16 v[100:103], v[124:127], v[176:179], v[100:103]
	v_mfma_f32_16x16x32_bf16 v[88:91], v[132:135], v[176:179], v[88:91]
	v_mfma_f32_16x16x32_bf16 v[84:87], v[124:127], v[184:187], v[84:87]
	v_mfma_f32_16x16x32_bf16 v[72:75], v[132:135], v[184:187], v[72:75]
	v_mfma_f32_16x16x32_bf16 v[136:139], v[128:131], v[164:167], v[136:139]
	v_mfma_f32_16x16x32_bf16 v[120:123], v[140:143], v[164:167], v[120:123]
	v_mfma_f32_16x16x32_bf16 v[116:119], v[128:131], v[172:175], v[116:119]
	v_mfma_f32_16x16x32_bf16 v[104:107], v[140:143], v[172:175], v[104:107]
	v_mfma_f32_16x16x32_bf16 v[100:103], v[128:131], v[180:183], v[100:103]
	v_mfma_f32_16x16x32_bf16 v[88:91], v[140:143], v[180:183], v[88:91]
	v_mfma_f32_16x16x32_bf16 v[84:87], v[128:131], v[188:191], v[84:87]
	v_mfma_f32_16x16x32_bf16 v[72:75], v[140:143], v[188:191], v[72:75]
	s_setprio 0
	s_setprio 1
	v_mfma_f32_16x16x32_bf16 v[112:115], v[144:147], v[160:163], v[112:115]
	v_mfma_f32_16x16x32_bf16 v[108:111], v[152:155], v[160:163], v[108:111]
	v_mfma_f32_16x16x32_bf16 v[96:99], v[144:147], v[168:171], v[96:99]
	v_mfma_f32_16x16x32_bf16 v[92:95], v[152:155], v[168:171], v[92:95]
	v_mfma_f32_16x16x32_bf16 v[80:83], v[144:147], v[176:179], v[80:83]
	v_mfma_f32_16x16x32_bf16 v[76:79], v[152:155], v[176:179], v[76:79]
	v_mfma_f32_16x16x32_bf16 v[68:71], v[144:147], v[184:187], v[68:71]
	v_mfma_f32_16x16x32_bf16 v[64:67], v[152:155], v[184:187], v[64:67]
	v_mfma_f32_16x16x32_bf16 v[112:115], v[148:151], v[164:167], v[112:115]
	v_mfma_f32_16x16x32_bf16 v[108:111], v[156:159], v[164:167], v[108:111]
	v_mfma_f32_16x16x32_bf16 v[96:99], v[148:151], v[172:175], v[96:99]
	v_mfma_f32_16x16x32_bf16 v[92:95], v[156:159], v[172:175], v[92:95]
	v_mfma_f32_16x16x32_bf16 v[80:83], v[148:151], v[180:183], v[80:83]
	v_mfma_f32_16x16x32_bf16 v[76:79], v[156:159], v[180:183], v[76:79]
	v_mfma_f32_16x16x32_bf16 v[68:71], v[148:151], v[188:191], v[68:71]
	v_mfma_f32_16x16x32_bf16 v[64:67], v[156:159], v[188:191], v[64:67]
	s_setprio 0
	s_barrier
	s_add_i32 s0, s24, s40
	v_lshl_add_u64 v[192:193], v[192:193], 0, s[54:55]
	s_mov_b32 m0, s0
	ds_read_b128 v[160:163], v253 offset:49152
	ds_read_b128 v[164:167], v253 offset:50176
	ds_read_b128 v[168:171], v253 offset:51200
	ds_read_b128 v[172:175], v253 offset:52224
	ds_read_b128 v[176:179], v253 offset:53248
	ds_read_b128 v[180:183], v253 offset:54272
	ds_read_b128 v[184:187], v253 offset:55296
	ds_read_b128 v[188:191], v253 offset:56320
	global_load_lds_dwordx4 v[192:193], off
	s_add_i32 m0, s0, 0x2000
	s_add_u32 s0, s28, 0x160080
	v_lshl_add_u64 v[192:193], v[194:195], 0, s[54:55]
	s_addc_u32 s1, s29, 0
	s_add_i32 s24, s25, s40
	global_load_lds_dwordx4 v[192:193], off
	v_lshl_add_u64 v[192:193], s[0:1], 0, v[198:199]
	s_mov_b32 m0, s24
	s_nop 0
	global_load_lds_dwordx4 v[192:193], off
	v_lshl_add_u64 v[192:193], s[0:1], 0, v[212:213]
	s_add_i32 m0, s24, 0x2000
	s_nop 0
	global_load_lds_dwordx4 v[192:193], off
	v_lshl_add_u64 v[192:193], v[196:197], 0, s[54:55]
	s_mov_b32 m0, s47
	s_nop 0
	global_load_lds_dwordx4 v[192:193], off
	v_lshl_add_u64 v[192:193], v[218:219], 0, s[54:55]
	s_mov_b32 m0, s48
	s_nop 0
	global_load_lds_dwordx4 v[192:193], off
	s_waitcnt vmcnt(8)
	s_waitcnt lgkmcnt(0)
	s_barrier
	s_setprio 1
	s_waitcnt lgkmcnt(0)
	v_mfma_f32_16x16x32_bf16 v[60:63], v[124:127], v[160:163], v[60:63]
	v_mfma_f32_16x16x32_bf16 v[56:59], v[132:135], v[160:163], v[56:59]
	v_mfma_f32_16x16x32_bf16 v[52:55], v[124:127], v[168:171], v[52:55]
	v_mfma_f32_16x16x32_bf16 v[40:43], v[132:135], v[168:171], v[40:43]
	v_mfma_f32_16x16x32_bf16 v[36:39], v[124:127], v[176:179], v[36:39]
	v_mfma_f32_16x16x32_bf16 v[24:27], v[132:135], v[176:179], v[24:27]
	v_mfma_f32_16x16x32_bf16 v[20:23], v[124:127], v[184:187], v[20:23]
	v_mfma_f32_16x16x32_bf16 v[8:11], v[132:135], v[184:187], v[8:11]
	v_mfma_f32_16x16x32_bf16 v[60:63], v[128:131], v[164:167], v[60:63]
	v_mfma_f32_16x16x32_bf16 v[56:59], v[140:143], v[164:167], v[56:59]
	v_mfma_f32_16x16x32_bf16 v[52:55], v[128:131], v[172:175], v[52:55]
	v_mfma_f32_16x16x32_bf16 v[40:43], v[140:143], v[172:175], v[40:43]
	v_mfma_f32_16x16x32_bf16 v[36:39], v[128:131], v[180:183], v[36:39]
	v_mfma_f32_16x16x32_bf16 v[24:27], v[140:143], v[180:183], v[24:27]
	v_mfma_f32_16x16x32_bf16 v[20:23], v[128:131], v[188:191], v[20:23]
	v_mfma_f32_16x16x32_bf16 v[8:11], v[140:143], v[188:191], v[8:11]
	s_setprio 0
	s_setprio 1
	v_mfma_f32_16x16x32_bf16 v[48:51], v[144:147], v[160:163], v[48:51]
	v_mfma_f32_16x16x32_bf16 v[44:47], v[152:155], v[160:163], v[44:47]
	v_mfma_f32_16x16x32_bf16 v[32:35], v[144:147], v[168:171], v[32:35]
	v_mfma_f32_16x16x32_bf16 v[28:31], v[152:155], v[168:171], v[28:31]
	v_mfma_f32_16x16x32_bf16 v[16:19], v[144:147], v[176:179], v[16:19]
	v_mfma_f32_16x16x32_bf16 v[12:15], v[152:155], v[176:179], v[12:15]
	v_mfma_f32_16x16x32_bf16 v[4:7], v[144:147], v[184:187], v[4:7]
	v_mfma_f32_16x16x32_bf16 v[0:3], v[152:155], v[184:187], v[0:3]
	v_mfma_f32_16x16x32_bf16 v[48:51], v[148:151], v[164:167], v[48:51]
	v_mfma_f32_16x16x32_bf16 v[44:47], v[156:159], v[164:167], v[44:47]
	v_mfma_f32_16x16x32_bf16 v[32:35], v[148:151], v[172:175], v[32:35]
	v_mfma_f32_16x16x32_bf16 v[28:31], v[156:159], v[172:175], v[28:31]
	v_mfma_f32_16x16x32_bf16 v[16:19], v[148:151], v[180:183], v[16:19]
	v_mfma_f32_16x16x32_bf16 v[12:15], v[156:159], v[180:183], v[12:15]
	v_mfma_f32_16x16x32_bf16 v[4:7], v[148:151], v[188:191], v[4:7]
	v_mfma_f32_16x16x32_bf16 v[0:3], v[156:159], v[188:191], v[0:3]
	s_setprio 0
	s_barrier
	s_add_i32 s79, s79, 2
	s_add_u32 s34, s34, 0x100
	s_addc_u32 s35, s35, 0
	s_mov_b64 s[24:25], s[10:11]

.LBB0_102:
	s_ashr_i32 s17, s16, 31
	s_lshl_b64 s[0:1], s[16:17], 20
	s_add_u32 s18, s26, s0
	s_addc_u32 s19, s27, s1
	s_and_b64 s[0:1], s[6:7], exec
	s_cselect_b32 s17, s19, s25
	s_cselect_b32 s51, s18, s24
	s_ashr_i32 s15, s14, 31
	s_lshl_b64 s[0:1], s[14:15], 20
	s_add_u32 s20, s36, s0
	s_addc_u32 s21, s37, s1
	s_and_b64 s[0:1], s[6:7], exec
	s_cselect_b32 s15, s21, s29
	s_cselect_b32 s34, s20, s28
	s_add_u32 s24, s24, 0x80080
	s_addc_u32 s25, s25, 0
	s_add_u32 s35, s28, 0x100
	s_addc_u32 s52, s29, 0
	s_mov_b32 s61, -2
	s_add_u32 s0, s24, 0xfff80080
	s_addc_u32 s1, s25, -1
	s_add_i32 s59, 0, 0x10000
	s_cmp_eq_u32 s61, 28
	s_cselect_b32 s31, s17, s1
	s_cselect_b32 s30, s51, s0
	s_cselect_b32 s29, s15, s52
	s_cselect_b32 s28, s34, s35
	s_add_i32 s63, 0, 0x14000
	v_add_u32_e32 v154, s59, v147
	v_add_u32_e32 v170, s63, v147
	ds_read_b128 v[138:141], v154
	ds_read_b128 v[142:145], v154 offset:1024
	ds_read_b128 v[150:153], v154 offset:2048
	ds_read_b128 v[154:157], v154 offset:3072
	ds_read_b128 v[158:161], v170
	ds_read_b128 v[162:165], v170 offset:1024
	ds_read_b128 v[166:169], v170 offset:2048
	ds_read_b128 v[170:173], v170 offset:3072
	v_lshl_add_u64 v[220:221], s[24:25], 0, v[134:135]
	s_add_i32 m0, s40, 0xc000
	ds_read_b128 v[174:177], v149
	ds_read_b128 v[178:181], v149 offset:1024
	ds_read_b128 v[182:185], v149 offset:2048
	ds_read_b128 v[186:189], v149 offset:3072
	ds_read_b128 v[190:193], v149 offset:4096
	ds_read_b128 v[194:197], v149 offset:5120
	ds_read_b128 v[212:215], v149 offset:6144
	ds_read_b128 v[216:219], v149 offset:7168
	global_load_lds_dwordx4 v[220:221], off
	v_lshl_add_u64 v[220:221], s[24:25], 0, v[136:137]
	s_add_i32 m0, s40, 0xe000
	s_nop 0
	global_load_lds_dwordx4 v[220:221], off
	s_waitcnt vmcnt(63)
	s_waitcnt lgkmcnt(0)
	s_barrier
	s_setprio 1
	s_waitcnt lgkmcnt(0)
	v_mfma_f32_16x16x32_bf16 v[124:127], v[138:141], v[174:177], 0
	v_mfma_f32_16x16x32_bf16 v[116:119], v[150:153], v[174:177], 0
	v_mfma_f32_16x16x32_bf16 v[108:111], v[138:141], v[182:185], 0
	v_mfma_f32_16x16x32_bf16 v[96:99], v[150:153], v[182:185], 0
	v_mfma_f32_16x16x32_bf16 v[88:91], v[138:141], v[190:193], 0
	v_mfma_f32_16x16x32_bf16 v[80:83], v[150:153], v[190:193], 0
	v_mfma_f32_16x16x32_bf16 v[72:75], v[138:141], v[212:215], 0
	v_mfma_f32_16x16x32_bf16 v[64:67], v[150:153], v[212:215], 0
	v_mfma_f32_16x16x32_bf16 v[124:127], v[142:145], v[178:181], v[124:127]
	v_mfma_f32_16x16x32_bf16 v[116:119], v[154:157], v[178:181], v[116:119]
	v_mfma_f32_16x16x32_bf16 v[108:111], v[142:145], v[186:189], v[108:111]
	v_mfma_f32_16x16x32_bf16 v[96:99], v[154:157], v[186:189], v[96:99]
	v_mfma_f32_16x16x32_bf16 v[88:91], v[142:145], v[194:197], v[88:91]
	v_mfma_f32_16x16x32_bf16 v[80:83], v[154:157], v[194:197], v[80:83]
	v_mfma_f32_16x16x32_bf16 v[72:75], v[142:145], v[216:219], v[72:75]
	v_mfma_f32_16x16x32_bf16 v[64:67], v[154:157], v[216:219], v[64:67]
	s_setprio 0
	s_setprio 1
	v_mfma_f32_16x16x32_bf16 v[120:123], v[158:161], v[174:177], 0
	v_mfma_f32_16x16x32_bf16 v[112:115], v[166:169], v[174:177], 0
	v_mfma_f32_16x16x32_bf16 v[104:107], v[158:161], v[182:185], 0
	v_mfma_f32_16x16x32_bf16 v[100:103], v[166:169], v[182:185], 0
	v_mfma_f32_16x16x32_bf16 v[92:95], v[158:161], v[190:193], 0
	v_mfma_f32_16x16x32_bf16 v[84:87], v[166:169], v[190:193], 0
	v_mfma_f32_16x16x32_bf16 v[76:79], v[158:161], v[212:215], 0
	v_mfma_f32_16x16x32_bf16 v[68:71], v[166:169], v[212:215], 0
	v_mfma_f32_16x16x32_bf16 v[120:123], v[162:165], v[178:181], v[120:123]
	v_mfma_f32_16x16x32_bf16 v[112:115], v[170:173], v[178:181], v[112:115]
	v_mfma_f32_16x16x32_bf16 v[104:107], v[162:165], v[186:189], v[104:107]
	v_mfma_f32_16x16x32_bf16 v[100:103], v[170:173], v[186:189], v[100:103]
	v_mfma_f32_16x16x32_bf16 v[92:95], v[162:165], v[194:197], v[92:95]
	v_mfma_f32_16x16x32_bf16 v[84:87], v[170:173], v[194:197], v[84:87]
	v_mfma_f32_16x16x32_bf16 v[76:79], v[162:165], v[216:219], v[76:79]
	v_mfma_f32_16x16x32_bf16 v[68:71], v[170:173], v[216:219], v[68:71]
	s_setprio 0
	s_barrier
	s_add_i32 s0, s59, s38
	v_lshl_add_u64 v[220:221], s[28:29], 0, v[198:199]
	s_mov_b32 m0, s0
	ds_read_b128 v[174:177], v149 offset:16384
	ds_read_b128 v[178:181], v149 offset:17408
	ds_read_b128 v[182:185], v149 offset:18432
	ds_read_b128 v[186:189], v149 offset:19456
	ds_read_b128 v[190:193], v149 offset:20480
	ds_read_b128 v[194:197], v149 offset:21504
	ds_read_b128 v[212:215], v149 offset:22528
	ds_read_b128 v[216:219], v149 offset:23552
	global_load_lds_dwordx4 v[220:221], off
	s_add_i32 m0, s0, 0x2000
	s_add_u32 s0, s28, 0x80000
	v_lshl_add_u64 v[222:223], s[28:29], 0, v[128:129]
	s_addc_u32 s1, s29, 0
	s_add_i32 s59, s63, s38
	global_load_lds_dwordx4 v[222:223], off
	v_lshl_add_u64 v[224:225], s[0:1], 0, v[198:199]
	s_mov_b32 m0, s59
	v_lshl_add_u64 v[226:227], s[30:31], 0, v[130:131]
	global_load_lds_dwordx4 v[224:225], off
	v_lshl_add_u64 v[224:225], s[0:1], 0, v[128:129]
	s_add_i32 m0, s59, 0x2000
	s_nop 0
	global_load_lds_dwordx4 v[224:225], off
	v_lshl_add_u64 v[224:225], s[30:31], 0, v[132:133]
	s_mov_b32 m0, s40
	s_nop 0
	global_load_lds_dwordx4 v[224:225], off
	s_mov_b32 m0, s41
	s_nop 0
	global_load_lds_dwordx4 v[226:227], off
	s_waitcnt vmcnt(8)
	s_waitcnt lgkmcnt(0)
	s_barrier
	s_setprio 1
	s_waitcnt lgkmcnt(0)
	v_mfma_f32_16x16x32_bf16 v[56:59], v[138:141], v[174:177], 0
	v_mfma_f32_16x16x32_bf16 v[48:51], v[150:153], v[174:177], 0
	v_mfma_f32_16x16x32_bf16 v[40:43], v[138:141], v[182:185], 0
	v_mfma_f32_16x16x32_bf16 v[32:35], v[150:153], v[182:185], 0
	v_mfma_f32_16x16x32_bf16 v[24:27], v[138:141], v[190:193], 0
	v_mfma_f32_16x16x32_bf16 v[16:19], v[150:153], v[190:193], 0
	v_mfma_f32_16x16x32_bf16 v[8:11], v[138:141], v[212:215], 0
	v_mfma_f32_16x16x32_bf16 v[0:3], v[150:153], v[212:215], 0
	v_mfma_f32_16x16x32_bf16 v[56:59], v[142:145], v[178:181], v[56:59]
	v_mfma_f32_16x16x32_bf16 v[48:51], v[154:157], v[178:181], v[48:51]
	v_mfma_f32_16x16x32_bf16 v[40:43], v[142:145], v[186:189], v[40:43]
	v_mfma_f32_16x16x32_bf16 v[32:35], v[154:157], v[186:189], v[32:35]
	v_mfma_f32_16x16x32_bf16 v[24:27], v[142:145], v[194:197], v[24:27]
	v_mfma_f32_16x16x32_bf16 v[16:19], v[154:157], v[194:197], v[16:19]
	v_mfma_f32_16x16x32_bf16 v[8:11], v[142:145], v[216:219], v[8:11]
	v_mfma_f32_16x16x32_bf16 v[0:3], v[154:157], v[216:219], v[0:3]
	s_setprio 0
	s_setprio 1
	v_mfma_f32_16x16x32_bf16 v[60:63], v[158:161], v[174:177], 0
	v_mfma_f32_16x16x32_bf16 v[52:55], v[166:169], v[174:177], 0
	v_mfma_f32_16x16x32_bf16 v[44:47], v[158:161], v[182:185], 0
	v_mfma_f32_16x16x32_bf16 v[36:39], v[166:169], v[182:185], 0
	v_mfma_f32_16x16x32_bf16 v[28:31], v[158:161], v[190:193], 0
	v_mfma_f32_16x16x32_bf16 v[20:23], v[166:169], v[190:193], 0
	v_mfma_f32_16x16x32_bf16 v[12:15], v[158:161], v[212:215], 0
	v_mfma_f32_16x16x32_bf16 v[4:7], v[166:169], v[212:215], 0
	v_mfma_f32_16x16x32_bf16 v[60:63], v[162:165], v[178:181], v[60:63]
	v_mfma_f32_16x16x32_bf16 v[52:55], v[170:173], v[178:181], v[52:55]
	v_mfma_f32_16x16x32_bf16 v[44:47], v[162:165], v[186:189], v[44:47]
	v_mfma_f32_16x16x32_bf16 v[36:39], v[170:173], v[186:189], v[36:39]
	v_mfma_f32_16x16x32_bf16 v[28:31], v[162:165], v[194:197], v[28:31]
	v_mfma_f32_16x16x32_bf16 v[20:23], v[170:173], v[194:197], v[20:23]
	v_mfma_f32_16x16x32_bf16 v[12:15], v[162:165], v[216:219], v[12:15]
	v_mfma_f32_16x16x32_bf16 v[4:7], v[170:173], v[216:219], v[4:7]
	s_setprio 0
	s_barrier
	s_add_i32 s59, 0, 0x18000
	s_add_i32 s63, 0, 0x1c000
	v_add_u32_e32 v154, s59, v147
	v_add_u32_e32 v170, s63, v147
	ds_read_b128 v[138:141], v154
	ds_read_b128 v[142:145], v154 offset:1024
	ds_read_b128 v[150:153], v154 offset:2048
	ds_read_b128 v[154:157], v154 offset:3072
	ds_read_b128 v[158:161], v170
	ds_read_b128 v[162:165], v170 offset:1024
	ds_read_b128 v[166:169], v170 offset:2048
	ds_read_b128 v[170:173], v170 offset:3072
	s_add_u32 s0, s30, 0x80000
	s_addc_u32 s1, s31, 0
	s_mov_b32 m0, s42
	v_lshl_add_u64 v[228:229], s[0:1], 0, v[132:133]
	ds_read_b128 v[174:177], v149 offset:32768
	ds_read_b128 v[178:181], v149 offset:33792
	ds_read_b128 v[182:185], v149 offset:34816
	ds_read_b128 v[186:189], v149 offset:35840
	ds_read_b128 v[190:193], v149 offset:36864
	ds_read_b128 v[194:197], v149 offset:37888
	ds_read_b128 v[212:215], v149 offset:38912
	ds_read_b128 v[216:219], v149 offset:39936
	global_load_lds_dwordx4 v[228:229], off
	v_lshl_add_u64 v[228:229], s[0:1], 0, v[130:131]
	s_mov_b32 m0, s43
	s_nop 0
	global_load_lds_dwordx4 v[228:229], off
	s_waitcnt vmcnt(8)
	s_waitcnt lgkmcnt(0)
	s_barrier
	s_setprio 1
	s_waitcnt lgkmcnt(0)
	v_mfma_f32_16x16x32_bf16 v[124:127], v[138:141], v[174:177], v[124:127]
	v_mfma_f32_16x16x32_bf16 v[116:119], v[150:153], v[174:177], v[116:119]
	v_mfma_f32_16x16x32_bf16 v[108:111], v[138:141], v[182:185], v[108:111]
	v_mfma_f32_16x16x32_bf16 v[96:99], v[150:153], v[182:185], v[96:99]
	v_mfma_f32_16x16x32_bf16 v[88:91], v[138:141], v[190:193], v[88:91]
	v_mfma_f32_16x16x32_bf16 v[80:83], v[150:153], v[190:193], v[80:83]
	v_mfma_f32_16x16x32_bf16 v[72:75], v[138:141], v[212:215], v[72:75]
	v_mfma_f32_16x16x32_bf16 v[64:67], v[150:153], v[212:215], v[64:67]
	v_mfma_f32_16x16x32_bf16 v[124:127], v[142:145], v[178:181], v[124:127]
	v_mfma_f32_16x16x32_bf16 v[116:119], v[154:157], v[178:181], v[116:119]
	v_mfma_f32_16x16x32_bf16 v[108:111], v[142:145], v[186:189], v[108:111]
	v_mfma_f32_16x16x32_bf16 v[96:99], v[154:157], v[186:189], v[96:99]
	v_mfma_f32_16x16x32_bf16 v[88:91], v[142:145], v[194:197], v[88:91]
	v_mfma_f32_16x16x32_bf16 v[80:83], v[154:157], v[194:197], v[80:83]
	v_mfma_f32_16x16x32_bf16 v[72:75], v[142:145], v[216:219], v[72:75]
	v_mfma_f32_16x16x32_bf16 v[64:67], v[154:157], v[216:219], v[64:67]
	s_setprio 0
	s_setprio 1
	v_mfma_f32_16x16x32_bf16 v[120:123], v[158:161], v[174:177], v[120:123]
	v_mfma_f32_16x16x32_bf16 v[112:115], v[166:169], v[174:177], v[112:115]
	v_mfma_f32_16x16x32_bf16 v[104:107], v[158:161], v[182:185], v[104:107]
	v_mfma_f32_16x16x32_bf16 v[100:103], v[166:169], v[182:185], v[100:103]
	v_mfma_f32_16x16x32_bf16 v[92:95], v[158:161], v[190:193], v[92:95]
	v_mfma_f32_16x16x32_bf16 v[84:87], v[166:169], v[190:193], v[84:87]
	v_mfma_f32_16x16x32_bf16 v[76:79], v[158:161], v[212:215], v[76:79]
	v_mfma_f32_16x16x32_bf16 v[68:71], v[166:169], v[212:215], v[68:71]
	v_mfma_f32_16x16x32_bf16 v[120:123], v[162:165], v[178:181], v[120:123]
	v_mfma_f32_16x16x32_bf16 v[112:115], v[170:173], v[178:181], v[112:115]
	v_mfma_f32_16x16x32_bf16 v[104:107], v[162:165], v[186:189], v[104:107]
	v_mfma_f32_16x16x32_bf16 v[100:103], v[170:173], v[186:189], v[100:103]
	v_mfma_f32_16x16x32_bf16 v[92:95], v[162:165], v[194:197], v[92:95]
	v_mfma_f32_16x16x32_bf16 v[84:87], v[170:173], v[194:197], v[84:87]
	v_mfma_f32_16x16x32_bf16 v[76:79], v[162:165], v[216:219], v[76:79]
	v_mfma_f32_16x16x32_bf16 v[68:71], v[170:173], v[216:219], v[68:71]
	s_setprio 0
	s_barrier
	s_add_i32 s0, s59, s38
	v_lshl_add_u64 v[220:221], v[220:221], 0, s[54:55]
	s_mov_b32 m0, s0
	ds_read_b128 v[174:177], v149 offset:49152
	ds_read_b128 v[178:181], v149 offset:50176
	ds_read_b128 v[182:185], v149 offset:51200
	ds_read_b128 v[186:189], v149 offset:52224
	ds_read_b128 v[190:193], v149 offset:53248
	ds_read_b128 v[194:197], v149 offset:54272
	ds_read_b128 v[212:215], v149 offset:55296
	ds_read_b128 v[216:219], v149 offset:56320
	global_load_lds_dwordx4 v[220:221], off
	s_add_i32 m0, s0, 0x2000
	s_add_u32 s0, s28, 0x80080
	v_lshl_add_u64 v[220:221], v[222:223], 0, s[54:55]
	s_addc_u32 s1, s29, 0
	s_add_i32 s28, s63, s38
	global_load_lds_dwordx4 v[220:221], off
	v_lshl_add_u64 v[220:221], s[0:1], 0, v[198:199]
	s_mov_b32 m0, s28
	s_nop 0
	global_load_lds_dwordx4 v[220:221], off
	v_lshl_add_u64 v[220:221], s[0:1], 0, v[128:129]
	s_add_i32 m0, s28, 0x2000
	s_nop 0
	global_load_lds_dwordx4 v[220:221], off
	v_lshl_add_u64 v[220:221], v[224:225], 0, s[54:55]
	s_mov_b32 m0, s47
	s_nop 0
	global_load_lds_dwordx4 v[220:221], off
	v_lshl_add_u64 v[220:221], v[226:227], 0, s[54:55]
	s_mov_b32 m0, s48
	s_nop 0
	global_load_lds_dwordx4 v[220:221], off
	s_waitcnt vmcnt(8)
	s_waitcnt lgkmcnt(0)
	s_barrier
	s_setprio 1
	s_waitcnt lgkmcnt(0)
	v_mfma_f32_16x16x32_bf16 v[56:59], v[138:141], v[174:177], v[56:59]
	v_mfma_f32_16x16x32_bf16 v[48:51], v[150:153], v[174:177], v[48:51]
	v_mfma_f32_16x16x32_bf16 v[40:43], v[138:141], v[182:185], v[40:43]
	v_mfma_f32_16x16x32_bf16 v[32:35], v[150:153], v[182:185], v[32:35]
	v_mfma_f32_16x16x32_bf16 v[24:27], v[138:141], v[190:193], v[24:27]
	v_mfma_f32_16x16x32_bf16 v[16:19], v[150:153], v[190:193], v[16:19]
	v_mfma_f32_16x16x32_bf16 v[8:11], v[138:141], v[212:215], v[8:11]
	v_mfma_f32_16x16x32_bf16 v[0:3], v[150:153], v[212:215], v[0:3]
	v_mfma_f32_16x16x32_bf16 v[56:59], v[142:145], v[178:181], v[56:59]
	v_mfma_f32_16x16x32_bf16 v[48:51], v[154:157], v[178:181], v[48:51]
	v_mfma_f32_16x16x32_bf16 v[40:43], v[142:145], v[186:189], v[40:43]
	v_mfma_f32_16x16x32_bf16 v[32:35], v[154:157], v[186:189], v[32:35]
	v_mfma_f32_16x16x32_bf16 v[24:27], v[142:145], v[194:197], v[24:27]
	v_mfma_f32_16x16x32_bf16 v[16:19], v[154:157], v[194:197], v[16:19]
	v_mfma_f32_16x16x32_bf16 v[8:11], v[142:145], v[216:219], v[8:11]
	v_mfma_f32_16x16x32_bf16 v[0:3], v[154:157], v[216:219], v[0:3]
	s_setprio 0
	s_setprio 1
	v_mfma_f32_16x16x32_bf16 v[60:63], v[158:161], v[174:177], v[60:63]
	v_mfma_f32_16x16x32_bf16 v[52:55], v[166:169], v[174:177], v[52:55]
	v_mfma_f32_16x16x32_bf16 v[44:47], v[158:161], v[182:185], v[44:47]
	v_mfma_f32_16x16x32_bf16 v[36:39], v[166:169], v[182:185], v[36:39]
	v_mfma_f32_16x16x32_bf16 v[28:31], v[158:161], v[190:193], v[28:31]
	v_mfma_f32_16x16x32_bf16 v[20:23], v[166:169], v[190:193], v[20:23]
	v_mfma_f32_16x16x32_bf16 v[12:15], v[158:161], v[212:215], v[12:15]
	v_mfma_f32_16x16x32_bf16 v[4:7], v[166:169], v[212:215], v[4:7]
	v_mfma_f32_16x16x32_bf16 v[60:63], v[162:165], v[178:181], v[60:63]
	v_mfma_f32_16x16x32_bf16 v[52:55], v[170:173], v[178:181], v[52:55]
	v_mfma_f32_16x16x32_bf16 v[44:47], v[162:165], v[186:189], v[44:47]
	v_mfma_f32_16x16x32_bf16 v[36:39], v[170:173], v[186:189], v[36:39]
	v_mfma_f32_16x16x32_bf16 v[28:31], v[162:165], v[194:197], v[28:31]
	v_mfma_f32_16x16x32_bf16 v[20:23], v[170:173], v[194:197], v[20:23]
	v_mfma_f32_16x16x32_bf16 v[12:15], v[162:165], v[216:219], v[12:15]
	v_mfma_f32_16x16x32_bf16 v[4:7], v[170:173], v[216:219], v[4:7]
	s_setprio 0
	s_barrier
	s_add_i32 s61, s61, 2
	s_add_u32 s24, s24, 0x100
	s_addc_u32 s25, s25, 0
	s_add_u32 s35, s35, 0x100
	s_addc_u32 s52, s52, 0

.LBB0_460:
	s_ashr_i32 s17, s16, 31
	s_lshl_b64 s[0:1], s[16:17], 20
	s_add_u32 s18, s26, s0
	s_addc_u32 s19, s27, s1
	s_and_b64 s[0:1], s[6:7], exec
	s_cselect_b32 s17, s19, s31
	s_cselect_b32 s61, s18, s30
	s_ashr_i32 s15, s14, 31
	s_lshl_b64 s[0:1], s[14:15], 20
	s_add_u32 s20, s40, s0
	s_addc_u32 s21, s41, s1
	s_and_b64 s[0:1], s[6:7], exec
	s_cselect_b32 s15, s21, s37
	s_cselect_b32 s34, s20, s36
	s_add_u32 s30, s30, 0x80080
	s_addc_u32 s31, s31, 0
	s_add_u32 s35, s36, 0x100
	s_addc_u32 s69, s37, 0
	s_mov_b32 s79, -2
	s_add_u32 s0, s30, 0xfff80080
	s_addc_u32 s1, s31, -1
	s_add_i32 s59, 0, 0x10000
	s_cmp_eq_u32 s79, 28
	s_cselect_b32 s39, s17, s1
	s_cselect_b32 s38, s61, s0
	s_cselect_b32 s37, s15, s69
	s_cselect_b32 s36, s34, s35
	s_add_i32 s63, 0, 0x14000
	v_add_u32_e32 v154, s59, v147
	v_add_u32_e32 v170, s63, v147
	ds_read_b128 v[138:141], v154
	ds_read_b128 v[142:145], v154 offset:1024
	ds_read_b128 v[150:153], v154 offset:2048
	ds_read_b128 v[154:157], v154 offset:3072
	ds_read_b128 v[158:161], v170
	ds_read_b128 v[162:165], v170 offset:1024
	ds_read_b128 v[166:169], v170 offset:2048
	ds_read_b128 v[170:173], v170 offset:3072
	v_lshl_add_u64 v[220:221], s[30:31], 0, v[134:135]
	s_add_i32 m0, s44, 0xc000
	ds_read_b128 v[174:177], v149
	ds_read_b128 v[178:181], v149 offset:1024
	ds_read_b128 v[182:185], v149 offset:2048
	ds_read_b128 v[186:189], v149 offset:3072
	ds_read_b128 v[190:193], v149 offset:4096
	ds_read_b128 v[194:197], v149 offset:5120
	ds_read_b128 v[212:215], v149 offset:6144
	ds_read_b128 v[216:219], v149 offset:7168
	global_load_lds_dwordx4 v[220:221], off
	v_lshl_add_u64 v[220:221], s[30:31], 0, v[136:137]
	s_add_i32 m0, s44, 0xe000
	s_nop 0
	global_load_lds_dwordx4 v[220:221], off
	s_waitcnt vmcnt(63)
	s_waitcnt lgkmcnt(0)
	s_barrier
	s_setprio 1
	s_waitcnt lgkmcnt(0)
	v_mfma_f32_16x16x32_bf16 v[124:127], v[138:141], v[174:177], 0
	v_mfma_f32_16x16x32_bf16 v[120:123], v[150:153], v[174:177], 0
	v_mfma_f32_16x16x32_bf16 v[108:111], v[138:141], v[182:185], 0
	v_mfma_f32_16x16x32_bf16 v[104:107], v[150:153], v[182:185], 0
	v_mfma_f32_16x16x32_bf16 v[92:95], v[138:141], v[190:193], 0
	v_mfma_f32_16x16x32_bf16 v[88:91], v[150:153], v[190:193], 0
	v_mfma_f32_16x16x32_bf16 v[76:79], v[138:141], v[212:215], 0
	v_mfma_f32_16x16x32_bf16 v[72:75], v[150:153], v[212:215], 0
	v_mfma_f32_16x16x32_bf16 v[124:127], v[142:145], v[178:181], v[124:127]
	v_mfma_f32_16x16x32_bf16 v[120:123], v[154:157], v[178:181], v[120:123]
	v_mfma_f32_16x16x32_bf16 v[108:111], v[142:145], v[186:189], v[108:111]
	v_mfma_f32_16x16x32_bf16 v[104:107], v[154:157], v[186:189], v[104:107]
	v_mfma_f32_16x16x32_bf16 v[92:95], v[142:145], v[194:197], v[92:95]
	v_mfma_f32_16x16x32_bf16 v[88:91], v[154:157], v[194:197], v[88:91]
	v_mfma_f32_16x16x32_bf16 v[76:79], v[142:145], v[216:219], v[76:79]
	v_mfma_f32_16x16x32_bf16 v[72:75], v[154:157], v[216:219], v[72:75]
	s_setprio 0
	s_setprio 1
	v_mfma_f32_16x16x32_bf16 v[116:119], v[158:161], v[174:177], 0
	v_mfma_f32_16x16x32_bf16 v[112:115], v[166:169], v[174:177], 0
	v_mfma_f32_16x16x32_bf16 v[100:103], v[158:161], v[182:185], 0
	v_mfma_f32_16x16x32_bf16 v[96:99], v[166:169], v[182:185], 0
	v_mfma_f32_16x16x32_bf16 v[84:87], v[158:161], v[190:193], 0
	v_mfma_f32_16x16x32_bf16 v[80:83], v[166:169], v[190:193], 0
	v_mfma_f32_16x16x32_bf16 v[68:71], v[158:161], v[212:215], 0
	v_mfma_f32_16x16x32_bf16 v[64:67], v[166:169], v[212:215], 0
	v_mfma_f32_16x16x32_bf16 v[116:119], v[162:165], v[178:181], v[116:119]
	v_mfma_f32_16x16x32_bf16 v[112:115], v[170:173], v[178:181], v[112:115]
	v_mfma_f32_16x16x32_bf16 v[100:103], v[162:165], v[186:189], v[100:103]
	v_mfma_f32_16x16x32_bf16 v[96:99], v[170:173], v[186:189], v[96:99]
	v_mfma_f32_16x16x32_bf16 v[84:87], v[162:165], v[194:197], v[84:87]
	v_mfma_f32_16x16x32_bf16 v[80:83], v[170:173], v[194:197], v[80:83]
	v_mfma_f32_16x16x32_bf16 v[68:71], v[162:165], v[216:219], v[68:71]
	v_mfma_f32_16x16x32_bf16 v[64:67], v[170:173], v[216:219], v[64:67]
	s_setprio 0
	s_barrier
	s_add_i32 s0, s59, s42
	v_lshl_add_u64 v[220:221], s[36:37], 0, v[198:199]
	s_mov_b32 m0, s0
	ds_read_b128 v[174:177], v149 offset:16384
	ds_read_b128 v[178:181], v149 offset:17408
	ds_read_b128 v[182:185], v149 offset:18432
	ds_read_b128 v[186:189], v149 offset:19456
	ds_read_b128 v[190:193], v149 offset:20480
	ds_read_b128 v[194:197], v149 offset:21504
	ds_read_b128 v[212:215], v149 offset:22528
	ds_read_b128 v[216:219], v149 offset:23552
	global_load_lds_dwordx4 v[220:221], off
	s_add_i32 m0, s0, 0x2000
	s_add_u32 s0, s36, 0x80000
	v_lshl_add_u64 v[222:223], s[36:37], 0, v[128:129]
	s_addc_u32 s1, s37, 0
	s_add_i32 s59, s63, s42
	global_load_lds_dwordx4 v[222:223], off
	v_lshl_add_u64 v[224:225], s[0:1], 0, v[198:199]
	s_mov_b32 m0, s59
	v_lshl_add_u64 v[226:227], s[38:39], 0, v[130:131]
	global_load_lds_dwordx4 v[224:225], off
	v_lshl_add_u64 v[224:225], s[0:1], 0, v[128:129]
	s_add_i32 m0, s59, 0x2000
	s_nop 0
	global_load_lds_dwordx4 v[224:225], off
	v_lshl_add_u64 v[224:225], s[38:39], 0, v[132:133]
	s_mov_b32 m0, s44
	s_nop 0
	global_load_lds_dwordx4 v[224:225], off
	s_mov_b32 m0, s45
	s_nop 0
	global_load_lds_dwordx4 v[226:227], off
	s_waitcnt vmcnt(8)
	s_waitcnt lgkmcnt(0)
	s_barrier
	s_setprio 1
	s_waitcnt lgkmcnt(0)
	v_mfma_f32_16x16x32_bf16 v[60:63], v[138:141], v[174:177], 0
	v_mfma_f32_16x16x32_bf16 v[56:59], v[150:153], v[174:177], 0
	v_mfma_f32_16x16x32_bf16 v[44:47], v[138:141], v[182:185], 0
	v_mfma_f32_16x16x32_bf16 v[40:43], v[150:153], v[182:185], 0
	v_mfma_f32_16x16x32_bf16 v[28:31], v[138:141], v[190:193], 0
	v_mfma_f32_16x16x32_bf16 v[24:27], v[150:153], v[190:193], 0
	v_mfma_f32_16x16x32_bf16 v[12:15], v[138:141], v[212:215], 0
	v_mfma_f32_16x16x32_bf16 v[8:11], v[150:153], v[212:215], 0
	v_mfma_f32_16x16x32_bf16 v[60:63], v[142:145], v[178:181], v[60:63]
	v_mfma_f32_16x16x32_bf16 v[56:59], v[154:157], v[178:181], v[56:59]
	v_mfma_f32_16x16x32_bf16 v[44:47], v[142:145], v[186:189], v[44:47]
	v_mfma_f32_16x16x32_bf16 v[40:43], v[154:157], v[186:189], v[40:43]
	v_mfma_f32_16x16x32_bf16 v[28:31], v[142:145], v[194:197], v[28:31]
	v_mfma_f32_16x16x32_bf16 v[24:27], v[154:157], v[194:197], v[24:27]
	v_mfma_f32_16x16x32_bf16 v[12:15], v[142:145], v[216:219], v[12:15]
	v_mfma_f32_16x16x32_bf16 v[8:11], v[154:157], v[216:219], v[8:11]
	s_setprio 0
	s_setprio 1
	v_mfma_f32_16x16x32_bf16 v[52:55], v[158:161], v[174:177], 0
	v_mfma_f32_16x16x32_bf16 v[48:51], v[166:169], v[174:177], 0
	v_mfma_f32_16x16x32_bf16 v[36:39], v[158:161], v[182:185], 0
	v_mfma_f32_16x16x32_bf16 v[32:35], v[166:169], v[182:185], 0
	v_mfma_f32_16x16x32_bf16 v[20:23], v[158:161], v[190:193], 0
	v_mfma_f32_16x16x32_bf16 v[16:19], v[166:169], v[190:193], 0
	v_mfma_f32_16x16x32_bf16 v[4:7], v[158:161], v[212:215], 0
	v_mfma_f32_16x16x32_bf16 v[0:3], v[166:169], v[212:215], 0
	v_mfma_f32_16x16x32_bf16 v[52:55], v[162:165], v[178:181], v[52:55]
	v_mfma_f32_16x16x32_bf16 v[48:51], v[170:173], v[178:181], v[48:51]
	v_mfma_f32_16x16x32_bf16 v[36:39], v[162:165], v[186:189], v[36:39]
	v_mfma_f32_16x16x32_bf16 v[32:35], v[170:173], v[186:189], v[32:35]
	v_mfma_f32_16x16x32_bf16 v[20:23], v[162:165], v[194:197], v[20:23]
	v_mfma_f32_16x16x32_bf16 v[16:19], v[170:173], v[194:197], v[16:19]
	v_mfma_f32_16x16x32_bf16 v[4:7], v[162:165], v[216:219], v[4:7]
	v_mfma_f32_16x16x32_bf16 v[0:3], v[170:173], v[216:219], v[0:3]
	s_setprio 0
	s_barrier
	s_add_i32 s59, 0, 0x18000
	s_add_i32 s63, 0, 0x1c000
	v_add_u32_e32 v154, s59, v147
	v_add_u32_e32 v170, s63, v147
	ds_read_b128 v[138:141], v154
	ds_read_b128 v[142:145], v154 offset:1024
	ds_read_b128 v[150:153], v154 offset:2048
	ds_read_b128 v[154:157], v154 offset:3072
	ds_read_b128 v[158:161], v170
	ds_read_b128 v[162:165], v170 offset:1024
	ds_read_b128 v[166:169], v170 offset:2048
	ds_read_b128 v[170:173], v170 offset:3072
	s_add_u32 s0, s38, 0x80000
	s_addc_u32 s1, s39, 0
	s_mov_b32 m0, s46
	v_lshl_add_u64 v[228:229], s[0:1], 0, v[132:133]
	ds_read_b128 v[174:177], v149 offset:32768
	ds_read_b128 v[178:181], v149 offset:33792
	ds_read_b128 v[182:185], v149 offset:34816
	ds_read_b128 v[186:189], v149 offset:35840
	ds_read_b128 v[190:193], v149 offset:36864
	ds_read_b128 v[194:197], v149 offset:37888
	ds_read_b128 v[212:215], v149 offset:38912
	ds_read_b128 v[216:219], v149 offset:39936
	global_load_lds_dwordx4 v[228:229], off
	v_lshl_add_u64 v[228:229], s[0:1], 0, v[130:131]
	s_mov_b32 m0, s47
	s_nop 0
	global_load_lds_dwordx4 v[228:229], off
	s_waitcnt vmcnt(8)
	s_waitcnt lgkmcnt(0)
	s_barrier
	s_setprio 1
	s_waitcnt lgkmcnt(0)
	v_mfma_f32_16x16x32_bf16 v[124:127], v[138:141], v[174:177], v[124:127]
	v_mfma_f32_16x16x32_bf16 v[120:123], v[150:153], v[174:177], v[120:123]
	v_mfma_f32_16x16x32_bf16 v[108:111], v[138:141], v[182:185], v[108:111]
	v_mfma_f32_16x16x32_bf16 v[104:107], v[150:153], v[182:185], v[104:107]
	v_mfma_f32_16x16x32_bf16 v[92:95], v[138:141], v[190:193], v[92:95]
	v_mfma_f32_16x16x32_bf16 v[88:91], v[150:153], v[190:193], v[88:91]
	v_mfma_f32_16x16x32_bf16 v[76:79], v[138:141], v[212:215], v[76:79]
	v_mfma_f32_16x16x32_bf16 v[72:75], v[150:153], v[212:215], v[72:75]
	v_mfma_f32_16x16x32_bf16 v[124:127], v[142:145], v[178:181], v[124:127]
	v_mfma_f32_16x16x32_bf16 v[120:123], v[154:157], v[178:181], v[120:123]
	v_mfma_f32_16x16x32_bf16 v[108:111], v[142:145], v[186:189], v[108:111]
	v_mfma_f32_16x16x32_bf16 v[104:107], v[154:157], v[186:189], v[104:107]
	v_mfma_f32_16x16x32_bf16 v[92:95], v[142:145], v[194:197], v[92:95]
	v_mfma_f32_16x16x32_bf16 v[88:91], v[154:157], v[194:197], v[88:91]
	v_mfma_f32_16x16x32_bf16 v[76:79], v[142:145], v[216:219], v[76:79]
	v_mfma_f32_16x16x32_bf16 v[72:75], v[154:157], v[216:219], v[72:75]
	s_setprio 0
	s_setprio 1
	v_mfma_f32_16x16x32_bf16 v[116:119], v[158:161], v[174:177], v[116:119]
	v_mfma_f32_16x16x32_bf16 v[112:115], v[166:169], v[174:177], v[112:115]
	v_mfma_f32_16x16x32_bf16 v[100:103], v[158:161], v[182:185], v[100:103]
	v_mfma_f32_16x16x32_bf16 v[96:99], v[166:169], v[182:185], v[96:99]
	v_mfma_f32_16x16x32_bf16 v[84:87], v[158:161], v[190:193], v[84:87]
	v_mfma_f32_16x16x32_bf16 v[80:83], v[166:169], v[190:193], v[80:83]
	v_mfma_f32_16x16x32_bf16 v[68:71], v[158:161], v[212:215], v[68:71]
	v_mfma_f32_16x16x32_bf16 v[64:67], v[166:169], v[212:215], v[64:67]
	v_mfma_f32_16x16x32_bf16 v[116:119], v[162:165], v[178:181], v[116:119]
	v_mfma_f32_16x16x32_bf16 v[112:115], v[170:173], v[178:181], v[112:115]
	v_mfma_f32_16x16x32_bf16 v[100:103], v[162:165], v[186:189], v[100:103]
	v_mfma_f32_16x16x32_bf16 v[96:99], v[170:173], v[186:189], v[96:99]
	v_mfma_f32_16x16x32_bf16 v[84:87], v[162:165], v[194:197], v[84:87]
	v_mfma_f32_16x16x32_bf16 v[80:83], v[170:173], v[194:197], v[80:83]
	v_mfma_f32_16x16x32_bf16 v[68:71], v[162:165], v[216:219], v[68:71]
	v_mfma_f32_16x16x32_bf16 v[64:67], v[170:173], v[216:219], v[64:67]
	s_setprio 0
	s_barrier
	s_add_i32 s0, s59, s42
	v_lshl_add_u64 v[220:221], v[220:221], 0, s[54:55]
	s_mov_b32 m0, s0
	ds_read_b128 v[174:177], v149 offset:49152
	ds_read_b128 v[178:181], v149 offset:50176
	ds_read_b128 v[182:185], v149 offset:51200
	ds_read_b128 v[186:189], v149 offset:52224
	ds_read_b128 v[190:193], v149 offset:53248
	ds_read_b128 v[194:197], v149 offset:54272
	ds_read_b128 v[212:215], v149 offset:55296
	ds_read_b128 v[216:219], v149 offset:56320
	global_load_lds_dwordx4 v[220:221], off
	s_add_i32 m0, s0, 0x2000
	s_add_u32 s0, s36, 0x80080
	v_lshl_add_u64 v[220:221], v[222:223], 0, s[54:55]
	s_addc_u32 s1, s37, 0
	s_add_i32 s36, s63, s42
	global_load_lds_dwordx4 v[220:221], off
	v_lshl_add_u64 v[220:221], s[0:1], 0, v[198:199]
	s_mov_b32 m0, s36
	s_nop 0
	global_load_lds_dwordx4 v[220:221], off
	v_lshl_add_u64 v[220:221], s[0:1], 0, v[128:129]
	s_add_i32 m0, s36, 0x2000
	s_nop 0
	global_load_lds_dwordx4 v[220:221], off
	v_lshl_add_u64 v[220:221], v[224:225], 0, s[54:55]
	s_mov_b32 m0, s49
	s_nop 0
	global_load_lds_dwordx4 v[220:221], off
	v_lshl_add_u64 v[220:221], v[226:227], 0, s[54:55]
	s_mov_b32 m0, s50
	s_nop 0
	global_load_lds_dwordx4 v[220:221], off
	s_waitcnt vmcnt(8)
	s_waitcnt lgkmcnt(0)
	s_barrier
	s_setprio 1
	s_waitcnt lgkmcnt(0)
	v_mfma_f32_16x16x32_bf16 v[60:63], v[138:141], v[174:177], v[60:63]
	v_mfma_f32_16x16x32_bf16 v[56:59], v[150:153], v[174:177], v[56:59]
	v_mfma_f32_16x16x32_bf16 v[44:47], v[138:141], v[182:185], v[44:47]
	v_mfma_f32_16x16x32_bf16 v[40:43], v[150:153], v[182:185], v[40:43]
	v_mfma_f32_16x16x32_bf16 v[28:31], v[138:141], v[190:193], v[28:31]
	v_mfma_f32_16x16x32_bf16 v[24:27], v[150:153], v[190:193], v[24:27]
	v_mfma_f32_16x16x32_bf16 v[12:15], v[138:141], v[212:215], v[12:15]
	v_mfma_f32_16x16x32_bf16 v[8:11], v[150:153], v[212:215], v[8:11]
	v_mfma_f32_16x16x32_bf16 v[60:63], v[142:145], v[178:181], v[60:63]
	v_mfma_f32_16x16x32_bf16 v[56:59], v[154:157], v[178:181], v[56:59]
	v_mfma_f32_16x16x32_bf16 v[44:47], v[142:145], v[186:189], v[44:47]
	v_mfma_f32_16x16x32_bf16 v[40:43], v[154:157], v[186:189], v[40:43]
	v_mfma_f32_16x16x32_bf16 v[28:31], v[142:145], v[194:197], v[28:31]
	v_mfma_f32_16x16x32_bf16 v[24:27], v[154:157], v[194:197], v[24:27]
	v_mfma_f32_16x16x32_bf16 v[12:15], v[142:145], v[216:219], v[12:15]
	v_mfma_f32_16x16x32_bf16 v[8:11], v[154:157], v[216:219], v[8:11]
	s_setprio 0
	s_setprio 1
	v_mfma_f32_16x16x32_bf16 v[52:55], v[158:161], v[174:177], v[52:55]
	v_mfma_f32_16x16x32_bf16 v[48:51], v[166:169], v[174:177], v[48:51]
	v_mfma_f32_16x16x32_bf16 v[36:39], v[158:161], v[182:185], v[36:39]
	v_mfma_f32_16x16x32_bf16 v[32:35], v[166:169], v[182:185], v[32:35]
	v_mfma_f32_16x16x32_bf16 v[20:23], v[158:161], v[190:193], v[20:23]
	v_mfma_f32_16x16x32_bf16 v[16:19], v[166:169], v[190:193], v[16:19]
	v_mfma_f32_16x16x32_bf16 v[4:7], v[158:161], v[212:215], v[4:7]
	v_mfma_f32_16x16x32_bf16 v[0:3], v[166:169], v[212:215], v[0:3]
	v_mfma_f32_16x16x32_bf16 v[52:55], v[162:165], v[178:181], v[52:55]
	v_mfma_f32_16x16x32_bf16 v[48:51], v[170:173], v[178:181], v[48:51]
	v_mfma_f32_16x16x32_bf16 v[36:39], v[162:165], v[186:189], v[36:39]
	v_mfma_f32_16x16x32_bf16 v[32:35], v[170:173], v[186:189], v[32:35]
	v_mfma_f32_16x16x32_bf16 v[20:23], v[162:165], v[194:197], v[20:23]
	v_mfma_f32_16x16x32_bf16 v[16:19], v[170:173], v[194:197], v[16:19]
	v_mfma_f32_16x16x32_bf16 v[4:7], v[162:165], v[216:219], v[4:7]
	v_mfma_f32_16x16x32_bf16 v[0:3], v[170:173], v[216:219], v[0:3]
	s_setprio 0
	s_barrier
	s_add_i32 s79, s79, 2
	s_add_u32 s30, s30, 0x100
	s_addc_u32 s31, s31, 0
	s_add_u32 s35, s35, 0x100
	s_addc_u32 s69, s69, 0

.LBB0_492:
	s_add_u32 s34, s30, 0x100
	s_addc_u32 s35, s31, 0
	s_mov_b32 s81, -2
	s_waitcnt lgkmcnt(0)
	s_add_u32 s30, s28, 0x100
	s_addc_u32 s31, s29, 0
	s_add_i32 s0, 0, 0x10000
	s_cmpk_eq_i32 s81, 0x54
	s_cselect_b32 s39, s11, s31
	s_cselect_b32 s38, s10, s30
	s_cselect_b32 s37, s21, s35
	s_cselect_b32 s36, s20, s34
	s_add_i32 s59, 0, 0x14000
	v_add_u32_e32 v140, s0, v195
	v_add_u32_e32 v156, s59, v195
	ds_read_b128 v[120:123], v140
	ds_read_b128 v[124:127], v140 offset:1024
	ds_read_b128 v[128:131], v140 offset:2048
	ds_read_b128 v[140:143], v140 offset:3072
	ds_read_b128 v[144:147], v156
	ds_read_b128 v[148:151], v156 offset:1024
	ds_read_b128 v[152:155], v156 offset:2048
	ds_read_b128 v[156:159], v156 offset:3072
	v_lshl_add_u64 v[216:217], s[28:29], 0, v[178:179]
	s_add_i32 m0, s45, 0xc000
	ds_read_b128 v[160:163], v197
	ds_read_b128 v[164:167], v197 offset:1024
	ds_read_b128 v[168:171], v197 offset:2048
	ds_read_b128 v[172:175], v197 offset:3072
	ds_read_b128 v[182:185], v197 offset:4096
	ds_read_b128 v[186:189], v197 offset:5120
	ds_read_b128 v[190:193], v197 offset:6144
	ds_read_b128 v[212:215], v197 offset:7168
	global_load_lds_dwordx4 v[216:217], off
	v_lshl_add_u64 v[216:217], s[28:29], 0, v[180:181]
	s_add_i32 m0, s45, 0xe000
	s_nop 0
	global_load_lds_dwordx4 v[216:217], off
	s_waitcnt vmcnt(63)
	s_waitcnt lgkmcnt(0)
	s_barrier
	s_setprio 1
	s_waitcnt lgkmcnt(0)
	v_mfma_f32_16x16x32_bf16 v[136:139], v[120:123], v[160:163], 0
	v_mfma_f32_16x16x32_bf16 v[132:135], v[128:131], v[160:163], 0
	v_mfma_f32_16x16x32_bf16 v[108:111], v[120:123], v[168:171], 0
	v_mfma_f32_16x16x32_bf16 v[104:107], v[128:131], v[168:171], 0
	v_mfma_f32_16x16x32_bf16 v[92:95], v[120:123], v[182:185], 0
	v_mfma_f32_16x16x32_bf16 v[88:91], v[128:131], v[182:185], 0
	v_mfma_f32_16x16x32_bf16 v[76:79], v[120:123], v[190:193], 0
	v_mfma_f32_16x16x32_bf16 v[72:75], v[128:131], v[190:193], 0
	v_mfma_f32_16x16x32_bf16 v[136:139], v[124:127], v[164:167], v[136:139]
	v_mfma_f32_16x16x32_bf16 v[132:135], v[140:143], v[164:167], v[132:135]
	v_mfma_f32_16x16x32_bf16 v[108:111], v[124:127], v[172:175], v[108:111]
	v_mfma_f32_16x16x32_bf16 v[104:107], v[140:143], v[172:175], v[104:107]
	v_mfma_f32_16x16x32_bf16 v[92:95], v[124:127], v[186:189], v[92:95]
	v_mfma_f32_16x16x32_bf16 v[88:91], v[140:143], v[186:189], v[88:91]
	v_mfma_f32_16x16x32_bf16 v[76:79], v[124:127], v[212:215], v[76:79]
	v_mfma_f32_16x16x32_bf16 v[72:75], v[140:143], v[212:215], v[72:75]
	s_setprio 0
	s_setprio 1
	v_mfma_f32_16x16x32_bf16 v[116:119], v[144:147], v[160:163], 0
	v_mfma_f32_16x16x32_bf16 v[112:115], v[152:155], v[160:163], 0
	v_mfma_f32_16x16x32_bf16 v[100:103], v[144:147], v[168:171], 0
	v_mfma_f32_16x16x32_bf16 v[96:99], v[152:155], v[168:171], 0
	v_mfma_f32_16x16x32_bf16 v[84:87], v[144:147], v[182:185], 0
	v_mfma_f32_16x16x32_bf16 v[80:83], v[152:155], v[182:185], 0
	v_mfma_f32_16x16x32_bf16 v[68:71], v[144:147], v[190:193], 0
	v_mfma_f32_16x16x32_bf16 v[64:67], v[152:155], v[190:193], 0
	v_mfma_f32_16x16x32_bf16 v[116:119], v[148:151], v[164:167], v[116:119]
	v_mfma_f32_16x16x32_bf16 v[112:115], v[156:159], v[164:167], v[112:115]
	v_mfma_f32_16x16x32_bf16 v[100:103], v[148:151], v[172:175], v[100:103]
	v_mfma_f32_16x16x32_bf16 v[96:99], v[156:159], v[172:175], v[96:99]
	v_mfma_f32_16x16x32_bf16 v[84:87], v[148:151], v[186:189], v[84:87]
	v_mfma_f32_16x16x32_bf16 v[80:83], v[156:159], v[186:189], v[80:83]
	v_mfma_f32_16x16x32_bf16 v[68:71], v[148:151], v[212:215], v[68:71]
	v_mfma_f32_16x16x32_bf16 v[64:67], v[156:159], v[212:215], v[64:67]
	s_setprio 0
	s_barrier
	s_add_i32 s0, s0, s44
	v_lshl_add_u64 v[216:217], s[36:37], 0, v[198:199]
	s_mov_b32 m0, s0
	ds_read_b128 v[160:163], v197 offset:16384
	ds_read_b128 v[164:167], v197 offset:17408
	ds_read_b128 v[168:171], v197 offset:18432
	ds_read_b128 v[172:175], v197 offset:19456
	ds_read_b128 v[182:185], v197 offset:20480
	ds_read_b128 v[186:189], v197 offset:21504
	ds_read_b128 v[190:193], v197 offset:22528
	ds_read_b128 v[212:215], v197 offset:23552
	global_load_lds_dwordx4 v[216:217], off
	s_add_i32 m0, s0, 0x2000
	s_add_u32 s0, s36, 0x160000
	v_lshl_add_u64 v[218:219], s[36:37], 0, v[176:177]
	s_addc_u32 s1, s37, 0
	s_add_i32 s28, s59, s44
	global_load_lds_dwordx4 v[218:219], off
	v_lshl_add_u64 v[220:221], s[0:1], 0, v[198:199]
	s_mov_b32 m0, s28
	v_lshl_add_u64 v[222:223], s[38:39], 0, v[176:177]
	global_load_lds_dwordx4 v[220:221], off
	v_lshl_add_u64 v[220:221], s[0:1], 0, v[176:177]
	s_add_i32 m0, s28, 0x2000
	s_nop 0
	global_load_lds_dwordx4 v[220:221], off
	v_lshl_add_u64 v[220:221], s[38:39], 0, v[198:199]
	s_mov_b32 m0, s45
	s_nop 0
	global_load_lds_dwordx4 v[220:221], off
	s_mov_b32 m0, s46
	s_nop 0
	global_load_lds_dwordx4 v[222:223], off
	s_waitcnt vmcnt(8)
	s_waitcnt lgkmcnt(0)
	s_barrier
	s_setprio 1
	s_waitcnt lgkmcnt(0)
	v_mfma_f32_16x16x32_bf16 v[60:63], v[120:123], v[160:163], 0
	v_mfma_f32_16x16x32_bf16 v[56:59], v[128:131], v[160:163], 0
	v_mfma_f32_16x16x32_bf16 v[44:47], v[120:123], v[168:171], 0
	v_mfma_f32_16x16x32_bf16 v[40:43], v[128:131], v[168:171], 0
	v_mfma_f32_16x16x32_bf16 v[28:31], v[120:123], v[182:185], 0
	v_mfma_f32_16x16x32_bf16 v[24:27], v[128:131], v[182:185], 0
	v_mfma_f32_16x16x32_bf16 v[12:15], v[120:123], v[190:193], 0
	v_mfma_f32_16x16x32_bf16 v[8:11], v[128:131], v[190:193], 0
	v_mfma_f32_16x16x32_bf16 v[60:63], v[124:127], v[164:167], v[60:63]
	v_mfma_f32_16x16x32_bf16 v[56:59], v[140:143], v[164:167], v[56:59]
	v_mfma_f32_16x16x32_bf16 v[44:47], v[124:127], v[172:175], v[44:47]
	v_mfma_f32_16x16x32_bf16 v[40:43], v[140:143], v[172:175], v[40:43]
	v_mfma_f32_16x16x32_bf16 v[28:31], v[124:127], v[186:189], v[28:31]
	v_mfma_f32_16x16x32_bf16 v[24:27], v[140:143], v[186:189], v[24:27]
	v_mfma_f32_16x16x32_bf16 v[12:15], v[124:127], v[212:215], v[12:15]
	v_mfma_f32_16x16x32_bf16 v[8:11], v[140:143], v[212:215], v[8:11]
	s_setprio 0
	s_setprio 1
	v_mfma_f32_16x16x32_bf16 v[52:55], v[144:147], v[160:163], 0
	v_mfma_f32_16x16x32_bf16 v[48:51], v[152:155], v[160:163], 0
	v_mfma_f32_16x16x32_bf16 v[36:39], v[144:147], v[168:171], 0
	v_mfma_f32_16x16x32_bf16 v[32:35], v[152:155], v[168:171], 0
	v_mfma_f32_16x16x32_bf16 v[20:23], v[144:147], v[182:185], 0
	v_mfma_f32_16x16x32_bf16 v[16:19], v[152:155], v[182:185], 0
	v_mfma_f32_16x16x32_bf16 v[4:7], v[144:147], v[190:193], 0
	v_mfma_f32_16x16x32_bf16 v[0:3], v[152:155], v[190:193], 0
	v_mfma_f32_16x16x32_bf16 v[52:55], v[148:151], v[164:167], v[52:55]
	v_mfma_f32_16x16x32_bf16 v[48:51], v[156:159], v[164:167], v[48:51]
	v_mfma_f32_16x16x32_bf16 v[36:39], v[148:151], v[172:175], v[36:39]
	v_mfma_f32_16x16x32_bf16 v[32:35], v[156:159], v[172:175], v[32:35]
	v_mfma_f32_16x16x32_bf16 v[20:23], v[148:151], v[186:189], v[20:23]
	v_mfma_f32_16x16x32_bf16 v[16:19], v[156:159], v[186:189], v[16:19]
	v_mfma_f32_16x16x32_bf16 v[4:7], v[148:151], v[212:215], v[4:7]
	v_mfma_f32_16x16x32_bf16 v[0:3], v[156:159], v[212:215], v[0:3]
	s_setprio 0
	s_barrier
	s_add_i32 s28, 0, 0x18000
	s_add_i32 s29, 0, 0x1c000
	v_add_u32_e32 v140, s28, v195
	v_add_u32_e32 v156, s29, v195
	ds_read_b128 v[120:123], v140
	ds_read_b128 v[124:127], v140 offset:1024
	ds_read_b128 v[128:131], v140 offset:2048
	ds_read_b128 v[140:143], v140 offset:3072
	ds_read_b128 v[144:147], v156
	ds_read_b128 v[148:151], v156 offset:1024
	ds_read_b128 v[152:155], v156 offset:2048
	ds_read_b128 v[156:159], v156 offset:3072
	s_add_u32 s0, s38, 0x160000
	s_addc_u32 s1, s39, 0
	s_mov_b32 m0, s47
	v_lshl_add_u64 v[224:225], s[0:1], 0, v[198:199]
	ds_read_b128 v[160:163], v197 offset:32768
	ds_read_b128 v[164:167], v197 offset:33792
	ds_read_b128 v[168:171], v197 offset:34816
	ds_read_b128 v[172:175], v197 offset:35840
	ds_read_b128 v[182:185], v197 offset:36864
	ds_read_b128 v[186:189], v197 offset:37888
	ds_read_b128 v[190:193], v197 offset:38912
	ds_read_b128 v[212:215], v197 offset:39936
	global_load_lds_dwordx4 v[224:225], off
	v_lshl_add_u64 v[224:225], s[0:1], 0, v[176:177]
	s_mov_b32 m0, s48
	s_nop 0
	global_load_lds_dwordx4 v[224:225], off
	s_waitcnt vmcnt(8)
	s_waitcnt lgkmcnt(0)
	s_barrier
	s_setprio 1
	s_waitcnt lgkmcnt(0)
	v_mfma_f32_16x16x32_bf16 v[136:139], v[120:123], v[160:163], v[136:139]
	v_mfma_f32_16x16x32_bf16 v[132:135], v[128:131], v[160:163], v[132:135]
	v_mfma_f32_16x16x32_bf16 v[108:111], v[120:123], v[168:171], v[108:111]
	v_mfma_f32_16x16x32_bf16 v[104:107], v[128:131], v[168:171], v[104:107]
	v_mfma_f32_16x16x32_bf16 v[92:95], v[120:123], v[182:185], v[92:95]
	v_mfma_f32_16x16x32_bf16 v[88:91], v[128:131], v[182:185], v[88:91]
	v_mfma_f32_16x16x32_bf16 v[76:79], v[120:123], v[190:193], v[76:79]
	v_mfma_f32_16x16x32_bf16 v[72:75], v[128:131], v[190:193], v[72:75]
	v_mfma_f32_16x16x32_bf16 v[136:139], v[124:127], v[164:167], v[136:139]
	v_mfma_f32_16x16x32_bf16 v[132:135], v[140:143], v[164:167], v[132:135]
	v_mfma_f32_16x16x32_bf16 v[108:111], v[124:127], v[172:175], v[108:111]
	v_mfma_f32_16x16x32_bf16 v[104:107], v[140:143], v[172:175], v[104:107]
	v_mfma_f32_16x16x32_bf16 v[92:95], v[124:127], v[186:189], v[92:95]
	v_mfma_f32_16x16x32_bf16 v[88:91], v[140:143], v[186:189], v[88:91]
	v_mfma_f32_16x16x32_bf16 v[76:79], v[124:127], v[212:215], v[76:79]
	v_mfma_f32_16x16x32_bf16 v[72:75], v[140:143], v[212:215], v[72:75]
	s_setprio 0
	s_setprio 1
	v_mfma_f32_16x16x32_bf16 v[116:119], v[144:147], v[160:163], v[116:119]
	v_mfma_f32_16x16x32_bf16 v[112:115], v[152:155], v[160:163], v[112:115]
	v_mfma_f32_16x16x32_bf16 v[100:103], v[144:147], v[168:171], v[100:103]
	v_mfma_f32_16x16x32_bf16 v[96:99], v[152:155], v[168:171], v[96:99]
	v_mfma_f32_16x16x32_bf16 v[84:87], v[144:147], v[182:185], v[84:87]
	v_mfma_f32_16x16x32_bf16 v[80:83], v[152:155], v[182:185], v[80:83]
	v_mfma_f32_16x16x32_bf16 v[68:71], v[144:147], v[190:193], v[68:71]
	v_mfma_f32_16x16x32_bf16 v[64:67], v[152:155], v[190:193], v[64:67]
	v_mfma_f32_16x16x32_bf16 v[116:119], v[148:151], v[164:167], v[116:119]
	v_mfma_f32_16x16x32_bf16 v[112:115], v[156:159], v[164:167], v[112:115]
	v_mfma_f32_16x16x32_bf16 v[100:103], v[148:151], v[172:175], v[100:103]
	v_mfma_f32_16x16x32_bf16 v[96:99], v[156:159], v[172:175], v[96:99]
	v_mfma_f32_16x16x32_bf16 v[84:87], v[148:151], v[186:189], v[84:87]
	v_mfma_f32_16x16x32_bf16 v[80:83], v[156:159], v[186:189], v[80:83]
	v_mfma_f32_16x16x32_bf16 v[68:71], v[148:151], v[212:215], v[68:71]
	v_mfma_f32_16x16x32_bf16 v[64:67], v[156:159], v[212:215], v[64:67]
	s_setprio 0
	s_barrier
	s_add_i32 s0, s28, s44
	v_lshl_add_u64 v[216:217], v[216:217], 0, s[54:55]
	s_mov_b32 m0, s0
	ds_read_b128 v[160:163], v197 offset:49152
	ds_read_b128 v[164:167], v197 offset:50176
	ds_read_b128 v[168:171], v197 offset:51200
	ds_read_b128 v[172:175], v197 offset:52224
	ds_read_b128 v[182:185], v197 offset:53248
	ds_read_b128 v[186:189], v197 offset:54272
	ds_read_b128 v[190:193], v197 offset:55296
	ds_read_b128 v[212:215], v197 offset:56320
	global_load_lds_dwordx4 v[216:217], off
	s_add_i32 m0, s0, 0x2000
	s_add_u32 s0, s36, 0x160080
	v_lshl_add_u64 v[216:217], v[218:219], 0, s[54:55]
	s_addc_u32 s1, s37, 0
	s_add_i32 s28, s29, s44
	global_load_lds_dwordx4 v[216:217], off
	v_lshl_add_u64 v[216:217], s[0:1], 0, v[198:199]
	s_mov_b32 m0, s28
	s_nop 0
	global_load_lds_dwordx4 v[216:217], off
	v_lshl_add_u64 v[216:217], s[0:1], 0, v[176:177]
	s_add_i32 m0, s28, 0x2000
	s_nop 0
	global_load_lds_dwordx4 v[216:217], off
	v_lshl_add_u64 v[216:217], v[220:221], 0, s[54:55]
	s_mov_b32 m0, s49
	s_nop 0
	global_load_lds_dwordx4 v[216:217], off
	v_lshl_add_u64 v[216:217], v[222:223], 0, s[54:55]
	s_mov_b32 m0, s50
	s_nop 0
	global_load_lds_dwordx4 v[216:217], off
	s_waitcnt vmcnt(8)
	s_waitcnt lgkmcnt(0)
	s_barrier
	s_setprio 1
	s_waitcnt lgkmcnt(0)
	v_mfma_f32_16x16x32_bf16 v[60:63], v[120:123], v[160:163], v[60:63]
	v_mfma_f32_16x16x32_bf16 v[56:59], v[128:131], v[160:163], v[56:59]
	v_mfma_f32_16x16x32_bf16 v[44:47], v[120:123], v[168:171], v[44:47]
	v_mfma_f32_16x16x32_bf16 v[40:43], v[128:131], v[168:171], v[40:43]
	v_mfma_f32_16x16x32_bf16 v[28:31], v[120:123], v[182:185], v[28:31]
	v_mfma_f32_16x16x32_bf16 v[24:27], v[128:131], v[182:185], v[24:27]
	v_mfma_f32_16x16x32_bf16 v[12:15], v[120:123], v[190:193], v[12:15]
	v_mfma_f32_16x16x32_bf16 v[8:11], v[128:131], v[190:193], v[8:11]
	v_mfma_f32_16x16x32_bf16 v[60:63], v[124:127], v[164:167], v[60:63]
	v_mfma_f32_16x16x32_bf16 v[56:59], v[140:143], v[164:167], v[56:59]
	v_mfma_f32_16x16x32_bf16 v[44:47], v[124:127], v[172:175], v[44:47]
	v_mfma_f32_16x16x32_bf16 v[40:43], v[140:143], v[172:175], v[40:43]
	v_mfma_f32_16x16x32_bf16 v[28:31], v[124:127], v[186:189], v[28:31]
	v_mfma_f32_16x16x32_bf16 v[24:27], v[140:143], v[186:189], v[24:27]
	v_mfma_f32_16x16x32_bf16 v[12:15], v[124:127], v[212:215], v[12:15]
	v_mfma_f32_16x16x32_bf16 v[8:11], v[140:143], v[212:215], v[8:11]
	s_setprio 0
	s_setprio 1
	v_mfma_f32_16x16x32_bf16 v[52:55], v[144:147], v[160:163], v[52:55]
	v_mfma_f32_16x16x32_bf16 v[48:51], v[152:155], v[160:163], v[48:51]
	v_mfma_f32_16x16x32_bf16 v[36:39], v[144:147], v[168:171], v[36:39]
	v_mfma_f32_16x16x32_bf16 v[32:35], v[152:155], v[168:171], v[32:35]
	v_mfma_f32_16x16x32_bf16 v[20:23], v[144:147], v[182:185], v[20:23]
	v_mfma_f32_16x16x32_bf16 v[16:19], v[152:155], v[182:185], v[16:19]
	v_mfma_f32_16x16x32_bf16 v[4:7], v[144:147], v[190:193], v[4:7]
	v_mfma_f32_16x16x32_bf16 v[0:3], v[152:155], v[190:193], v[0:3]
	v_mfma_f32_16x16x32_bf16 v[52:55], v[148:151], v[164:167], v[52:55]
	v_mfma_f32_16x16x32_bf16 v[48:51], v[156:159], v[164:167], v[48:51]
	v_mfma_f32_16x16x32_bf16 v[36:39], v[148:151], v[172:175], v[36:39]
	v_mfma_f32_16x16x32_bf16 v[32:35], v[156:159], v[172:175], v[32:35]
	v_mfma_f32_16x16x32_bf16 v[20:23], v[148:151], v[186:189], v[20:23]
	v_mfma_f32_16x16x32_bf16 v[16:19], v[156:159], v[186:189], v[16:19]
	v_mfma_f32_16x16x32_bf16 v[4:7], v[148:151], v[212:215], v[4:7]
	v_mfma_f32_16x16x32_bf16 v[0:3], v[156:159], v[212:215], v[0:3]
	s_setprio 0
	s_barrier
	s_add_i32 s81, s81, 2
	s_add_u32 s34, s34, 0x100
	s_addc_u32 s35, s35, 0
	s_mov_b64 s[28:29], s[30:31]

.LBB0_527:
	s_ashr_i32 s17, s16, 31
	s_lshl_b64 s[0:1], s[16:17], 20
	s_add_u32 s18, s26, s0
	s_addc_u32 s19, s27, s1
	s_and_b64 s[0:1], s[6:7], exec
	s_cselect_b32 s17, s19, s31
	s_cselect_b32 s51, s18, s30
	s_ashr_i32 s15, s14, 31
	s_lshl_b64 s[0:1], s[14:15], 20
	s_add_u32 s20, s70, s0
	s_addc_u32 s21, s71, s1
	s_and_b64 s[0:1], s[6:7], exec
	s_cselect_b32 s15, s21, s37
	s_cselect_b32 s34, s20, s36
	s_add_u32 s30, s30, 0x80080
	s_addc_u32 s31, s31, 0
	s_add_u32 s35, s36, 0x100
	s_addc_u32 s52, s37, 0
	s_mov_b32 s61, -2
	s_add_u32 s0, s30, 0xfff80080
	s_addc_u32 s1, s31, -1
	s_add_i32 s59, 0, 0x10000
	s_cmp_eq_u32 s61, 28
	s_cselect_b32 s39, s17, s1
	s_cselect_b32 s38, s51, s0
	s_cselect_b32 s37, s15, s52
	s_cselect_b32 s36, s34, s35
	s_add_i32 s63, 0, 0x14000
	v_add_u32_e32 v154, s59, v147
	v_add_u32_e32 v170, s63, v147
	ds_read_b128 v[138:141], v154
	ds_read_b128 v[142:145], v154 offset:1024
	ds_read_b128 v[150:153], v154 offset:2048
	ds_read_b128 v[154:157], v154 offset:3072
	ds_read_b128 v[158:161], v170
	ds_read_b128 v[162:165], v170 offset:1024
	ds_read_b128 v[166:169], v170 offset:2048
	ds_read_b128 v[170:173], v170 offset:3072
	v_lshl_add_u64 v[220:221], s[30:31], 0, v[134:135]
	s_add_i32 m0, s42, 0xc000
	ds_read_b128 v[174:177], v149
	ds_read_b128 v[178:181], v149 offset:1024
	ds_read_b128 v[182:185], v149 offset:2048
	ds_read_b128 v[186:189], v149 offset:3072
	ds_read_b128 v[190:193], v149 offset:4096
	ds_read_b128 v[194:197], v149 offset:5120
	ds_read_b128 v[212:215], v149 offset:6144
	ds_read_b128 v[216:219], v149 offset:7168
	global_load_lds_dwordx4 v[220:221], off
	v_lshl_add_u64 v[220:221], s[30:31], 0, v[136:137]
	s_add_i32 m0, s42, 0xe000
	s_nop 0
	global_load_lds_dwordx4 v[220:221], off
	s_waitcnt vmcnt(63)
	s_waitcnt lgkmcnt(0)
	s_barrier
	s_setprio 1
	s_waitcnt lgkmcnt(0)
	v_mfma_f32_16x16x32_bf16 v[124:127], v[138:141], v[174:177], 0
	v_mfma_f32_16x16x32_bf16 v[116:119], v[150:153], v[174:177], 0
	v_mfma_f32_16x16x32_bf16 v[108:111], v[138:141], v[182:185], 0
	v_mfma_f32_16x16x32_bf16 v[96:99], v[150:153], v[182:185], 0
	v_mfma_f32_16x16x32_bf16 v[88:91], v[138:141], v[190:193], 0
	v_mfma_f32_16x16x32_bf16 v[80:83], v[150:153], v[190:193], 0
	v_mfma_f32_16x16x32_bf16 v[72:75], v[138:141], v[212:215], 0
	v_mfma_f32_16x16x32_bf16 v[64:67], v[150:153], v[212:215], 0
	v_mfma_f32_16x16x32_bf16 v[124:127], v[142:145], v[178:181], v[124:127]
	v_mfma_f32_16x16x32_bf16 v[116:119], v[154:157], v[178:181], v[116:119]
	v_mfma_f32_16x16x32_bf16 v[108:111], v[142:145], v[186:189], v[108:111]
	v_mfma_f32_16x16x32_bf16 v[96:99], v[154:157], v[186:189], v[96:99]
	v_mfma_f32_16x16x32_bf16 v[88:91], v[142:145], v[194:197], v[88:91]
	v_mfma_f32_16x16x32_bf16 v[80:83], v[154:157], v[194:197], v[80:83]
	v_mfma_f32_16x16x32_bf16 v[72:75], v[142:145], v[216:219], v[72:75]
	v_mfma_f32_16x16x32_bf16 v[64:67], v[154:157], v[216:219], v[64:67]
	s_setprio 0
	s_setprio 1
	v_mfma_f32_16x16x32_bf16 v[120:123], v[158:161], v[174:177], 0
	v_mfma_f32_16x16x32_bf16 v[112:115], v[166:169], v[174:177], 0
	v_mfma_f32_16x16x32_bf16 v[104:107], v[158:161], v[182:185], 0
	v_mfma_f32_16x16x32_bf16 v[100:103], v[166:169], v[182:185], 0
	v_mfma_f32_16x16x32_bf16 v[92:95], v[158:161], v[190:193], 0
	v_mfma_f32_16x16x32_bf16 v[84:87], v[166:169], v[190:193], 0
	v_mfma_f32_16x16x32_bf16 v[76:79], v[158:161], v[212:215], 0
	v_mfma_f32_16x16x32_bf16 v[68:71], v[166:169], v[212:215], 0
	v_mfma_f32_16x16x32_bf16 v[120:123], v[162:165], v[178:181], v[120:123]
	v_mfma_f32_16x16x32_bf16 v[112:115], v[170:173], v[178:181], v[112:115]
	v_mfma_f32_16x16x32_bf16 v[104:107], v[162:165], v[186:189], v[104:107]
	v_mfma_f32_16x16x32_bf16 v[100:103], v[170:173], v[186:189], v[100:103]
	v_mfma_f32_16x16x32_bf16 v[92:95], v[162:165], v[194:197], v[92:95]
	v_mfma_f32_16x16x32_bf16 v[84:87], v[170:173], v[194:197], v[84:87]
	v_mfma_f32_16x16x32_bf16 v[76:79], v[162:165], v[216:219], v[76:79]
	v_mfma_f32_16x16x32_bf16 v[68:71], v[170:173], v[216:219], v[68:71]
	s_setprio 0
	s_barrier
	s_add_i32 s0, s59, s40
	v_lshl_add_u64 v[220:221], s[36:37], 0, v[198:199]
	s_mov_b32 m0, s0
	ds_read_b128 v[174:177], v149 offset:16384
	ds_read_b128 v[178:181], v149 offset:17408
	ds_read_b128 v[182:185], v149 offset:18432
	ds_read_b128 v[186:189], v149 offset:19456
	ds_read_b128 v[190:193], v149 offset:20480
	ds_read_b128 v[194:197], v149 offset:21504
	ds_read_b128 v[212:215], v149 offset:22528
	ds_read_b128 v[216:219], v149 offset:23552
	global_load_lds_dwordx4 v[220:221], off
	s_add_i32 m0, s0, 0x2000
	s_add_u32 s0, s36, 0x80000
	v_lshl_add_u64 v[222:223], s[36:37], 0, v[128:129]
	s_addc_u32 s1, s37, 0
	s_add_i32 s59, s63, s40
	global_load_lds_dwordx4 v[222:223], off
	v_lshl_add_u64 v[224:225], s[0:1], 0, v[198:199]
	s_mov_b32 m0, s59
	v_lshl_add_u64 v[226:227], s[38:39], 0, v[130:131]
	global_load_lds_dwordx4 v[224:225], off
	v_lshl_add_u64 v[224:225], s[0:1], 0, v[128:129]
	s_add_i32 m0, s59, 0x2000
	s_nop 0
	global_load_lds_dwordx4 v[224:225], off
	v_lshl_add_u64 v[224:225], s[38:39], 0, v[132:133]
	s_mov_b32 m0, s42
	s_nop 0
	global_load_lds_dwordx4 v[224:225], off
	s_mov_b32 m0, s43
	s_nop 0
	global_load_lds_dwordx4 v[226:227], off
	s_waitcnt vmcnt(8)
	s_waitcnt lgkmcnt(0)
	s_barrier
	s_setprio 1
	s_waitcnt lgkmcnt(0)
	v_mfma_f32_16x16x32_bf16 v[56:59], v[138:141], v[174:177], 0
	v_mfma_f32_16x16x32_bf16 v[48:51], v[150:153], v[174:177], 0
	v_mfma_f32_16x16x32_bf16 v[40:43], v[138:141], v[182:185], 0
	v_mfma_f32_16x16x32_bf16 v[32:35], v[150:153], v[182:185], 0
	v_mfma_f32_16x16x32_bf16 v[24:27], v[138:141], v[190:193], 0
	v_mfma_f32_16x16x32_bf16 v[16:19], v[150:153], v[190:193], 0
	v_mfma_f32_16x16x32_bf16 v[8:11], v[138:141], v[212:215], 0
	v_mfma_f32_16x16x32_bf16 v[0:3], v[150:153], v[212:215], 0
	v_mfma_f32_16x16x32_bf16 v[56:59], v[142:145], v[178:181], v[56:59]
	v_mfma_f32_16x16x32_bf16 v[48:51], v[154:157], v[178:181], v[48:51]
	v_mfma_f32_16x16x32_bf16 v[40:43], v[142:145], v[186:189], v[40:43]
	v_mfma_f32_16x16x32_bf16 v[32:35], v[154:157], v[186:189], v[32:35]
	v_mfma_f32_16x16x32_bf16 v[24:27], v[142:145], v[194:197], v[24:27]
	v_mfma_f32_16x16x32_bf16 v[16:19], v[154:157], v[194:197], v[16:19]
	v_mfma_f32_16x16x32_bf16 v[8:11], v[142:145], v[216:219], v[8:11]
	v_mfma_f32_16x16x32_bf16 v[0:3], v[154:157], v[216:219], v[0:3]
	s_setprio 0
	s_setprio 1
	v_mfma_f32_16x16x32_bf16 v[60:63], v[158:161], v[174:177], 0
	v_mfma_f32_16x16x32_bf16 v[52:55], v[166:169], v[174:177], 0
	v_mfma_f32_16x16x32_bf16 v[44:47], v[158:161], v[182:185], 0
	v_mfma_f32_16x16x32_bf16 v[36:39], v[166:169], v[182:185], 0
	v_mfma_f32_16x16x32_bf16 v[28:31], v[158:161], v[190:193], 0
	v_mfma_f32_16x16x32_bf16 v[20:23], v[166:169], v[190:193], 0
	v_mfma_f32_16x16x32_bf16 v[12:15], v[158:161], v[212:215], 0
	v_mfma_f32_16x16x32_bf16 v[4:7], v[166:169], v[212:215], 0
	v_mfma_f32_16x16x32_bf16 v[60:63], v[162:165], v[178:181], v[60:63]
	v_mfma_f32_16x16x32_bf16 v[52:55], v[170:173], v[178:181], v[52:55]
	v_mfma_f32_16x16x32_bf16 v[44:47], v[162:165], v[186:189], v[44:47]
	v_mfma_f32_16x16x32_bf16 v[36:39], v[170:173], v[186:189], v[36:39]
	v_mfma_f32_16x16x32_bf16 v[28:31], v[162:165], v[194:197], v[28:31]
	v_mfma_f32_16x16x32_bf16 v[20:23], v[170:173], v[194:197], v[20:23]
	v_mfma_f32_16x16x32_bf16 v[12:15], v[162:165], v[216:219], v[12:15]
	v_mfma_f32_16x16x32_bf16 v[4:7], v[170:173], v[216:219], v[4:7]
	s_setprio 0
	s_barrier
	s_add_i32 s59, 0, 0x18000
	s_add_i32 s63, 0, 0x1c000
	v_add_u32_e32 v154, s59, v147
	v_add_u32_e32 v170, s63, v147
	ds_read_b128 v[138:141], v154
	ds_read_b128 v[142:145], v154 offset:1024
	ds_read_b128 v[150:153], v154 offset:2048
	ds_read_b128 v[154:157], v154 offset:3072
	ds_read_b128 v[158:161], v170
	ds_read_b128 v[162:165], v170 offset:1024
	ds_read_b128 v[166:169], v170 offset:2048
	ds_read_b128 v[170:173], v170 offset:3072
	s_add_u32 s0, s38, 0x80000
	s_addc_u32 s1, s39, 0
	s_mov_b32 m0, s44
	v_lshl_add_u64 v[228:229], s[0:1], 0, v[132:133]
	ds_read_b128 v[174:177], v149 offset:32768
	ds_read_b128 v[178:181], v149 offset:33792
	ds_read_b128 v[182:185], v149 offset:34816
	ds_read_b128 v[186:189], v149 offset:35840
	ds_read_b128 v[190:193], v149 offset:36864
	ds_read_b128 v[194:197], v149 offset:37888
	ds_read_b128 v[212:215], v149 offset:38912
	ds_read_b128 v[216:219], v149 offset:39936
	global_load_lds_dwordx4 v[228:229], off
	v_lshl_add_u64 v[228:229], s[0:1], 0, v[130:131]
	s_mov_b32 m0, s45
	s_nop 0
	global_load_lds_dwordx4 v[228:229], off
	s_waitcnt vmcnt(8)
	s_waitcnt lgkmcnt(0)
	s_barrier
	s_setprio 1
	s_waitcnt lgkmcnt(0)
	v_mfma_f32_16x16x32_bf16 v[124:127], v[138:141], v[174:177], v[124:127]
	v_mfma_f32_16x16x32_bf16 v[116:119], v[150:153], v[174:177], v[116:119]
	v_mfma_f32_16x16x32_bf16 v[108:111], v[138:141], v[182:185], v[108:111]
	v_mfma_f32_16x16x32_bf16 v[96:99], v[150:153], v[182:185], v[96:99]
	v_mfma_f32_16x16x32_bf16 v[88:91], v[138:141], v[190:193], v[88:91]
	v_mfma_f32_16x16x32_bf16 v[80:83], v[150:153], v[190:193], v[80:83]
	v_mfma_f32_16x16x32_bf16 v[72:75], v[138:141], v[212:215], v[72:75]
	v_mfma_f32_16x16x32_bf16 v[64:67], v[150:153], v[212:215], v[64:67]
	v_mfma_f32_16x16x32_bf16 v[124:127], v[142:145], v[178:181], v[124:127]
	v_mfma_f32_16x16x32_bf16 v[116:119], v[154:157], v[178:181], v[116:119]
	v_mfma_f32_16x16x32_bf16 v[108:111], v[142:145], v[186:189], v[108:111]
	v_mfma_f32_16x16x32_bf16 v[96:99], v[154:157], v[186:189], v[96:99]
	v_mfma_f32_16x16x32_bf16 v[88:91], v[142:145], v[194:197], v[88:91]
	v_mfma_f32_16x16x32_bf16 v[80:83], v[154:157], v[194:197], v[80:83]
	v_mfma_f32_16x16x32_bf16 v[72:75], v[142:145], v[216:219], v[72:75]
	v_mfma_f32_16x16x32_bf16 v[64:67], v[154:157], v[216:219], v[64:67]
	s_setprio 0
	s_setprio 1
	v_mfma_f32_16x16x32_bf16 v[120:123], v[158:161], v[174:177], v[120:123]
	v_mfma_f32_16x16x32_bf16 v[112:115], v[166:169], v[174:177], v[112:115]
	v_mfma_f32_16x16x32_bf16 v[104:107], v[158:161], v[182:185], v[104:107]
	v_mfma_f32_16x16x32_bf16 v[100:103], v[166:169], v[182:185], v[100:103]
	v_mfma_f32_16x16x32_bf16 v[92:95], v[158:161], v[190:193], v[92:95]
	v_mfma_f32_16x16x32_bf16 v[84:87], v[166:169], v[190:193], v[84:87]
	v_mfma_f32_16x16x32_bf16 v[76:79], v[158:161], v[212:215], v[76:79]
	v_mfma_f32_16x16x32_bf16 v[68:71], v[166:169], v[212:215], v[68:71]
	v_mfma_f32_16x16x32_bf16 v[120:123], v[162:165], v[178:181], v[120:123]
	v_mfma_f32_16x16x32_bf16 v[112:115], v[170:173], v[178:181], v[112:115]
	v_mfma_f32_16x16x32_bf16 v[104:107], v[162:165], v[186:189], v[104:107]
	v_mfma_f32_16x16x32_bf16 v[100:103], v[170:173], v[186:189], v[100:103]
	v_mfma_f32_16x16x32_bf16 v[92:95], v[162:165], v[194:197], v[92:95]
	v_mfma_f32_16x16x32_bf16 v[84:87], v[170:173], v[194:197], v[84:87]
	v_mfma_f32_16x16x32_bf16 v[76:79], v[162:165], v[216:219], v[76:79]
	v_mfma_f32_16x16x32_bf16 v[68:71], v[170:173], v[216:219], v[68:71]
	s_setprio 0
	s_barrier
	s_add_i32 s0, s59, s40
	v_lshl_add_u64 v[220:221], v[220:221], 0, s[54:55]
	s_mov_b32 m0, s0
	ds_read_b128 v[174:177], v149 offset:49152
	ds_read_b128 v[178:181], v149 offset:50176
	ds_read_b128 v[182:185], v149 offset:51200
	ds_read_b128 v[186:189], v149 offset:52224
	ds_read_b128 v[190:193], v149 offset:53248
	ds_read_b128 v[194:197], v149 offset:54272
	ds_read_b128 v[212:215], v149 offset:55296
	ds_read_b128 v[216:219], v149 offset:56320
	global_load_lds_dwordx4 v[220:221], off
	s_add_i32 m0, s0, 0x2000
	s_add_u32 s0, s36, 0x80080
	v_lshl_add_u64 v[220:221], v[222:223], 0, s[54:55]
	s_addc_u32 s1, s37, 0
	s_add_i32 s36, s63, s40
	global_load_lds_dwordx4 v[220:221], off
	v_lshl_add_u64 v[220:221], s[0:1], 0, v[198:199]
	s_mov_b32 m0, s36
	s_nop 0
	global_load_lds_dwordx4 v[220:221], off
	v_lshl_add_u64 v[220:221], s[0:1], 0, v[128:129]
	s_add_i32 m0, s36, 0x2000
	s_nop 0
	global_load_lds_dwordx4 v[220:221], off
	v_lshl_add_u64 v[220:221], v[224:225], 0, s[54:55]
	s_mov_b32 m0, s47
	s_nop 0
	global_load_lds_dwordx4 v[220:221], off
	v_lshl_add_u64 v[220:221], v[226:227], 0, s[54:55]
	s_mov_b32 m0, s48
	s_nop 0
	global_load_lds_dwordx4 v[220:221], off
	s_waitcnt vmcnt(8)
	s_waitcnt lgkmcnt(0)
	s_barrier
	s_setprio 1
	s_waitcnt lgkmcnt(0)
	v_mfma_f32_16x16x32_bf16 v[56:59], v[138:141], v[174:177], v[56:59]
	v_mfma_f32_16x16x32_bf16 v[48:51], v[150:153], v[174:177], v[48:51]
	v_mfma_f32_16x16x32_bf16 v[40:43], v[138:141], v[182:185], v[40:43]
	v_mfma_f32_16x16x32_bf16 v[32:35], v[150:153], v[182:185], v[32:35]
	v_mfma_f32_16x16x32_bf16 v[24:27], v[138:141], v[190:193], v[24:27]
	v_mfma_f32_16x16x32_bf16 v[16:19], v[150:153], v[190:193], v[16:19]
	v_mfma_f32_16x16x32_bf16 v[8:11], v[138:141], v[212:215], v[8:11]
	v_mfma_f32_16x16x32_bf16 v[0:3], v[150:153], v[212:215], v[0:3]
	v_mfma_f32_16x16x32_bf16 v[56:59], v[142:145], v[178:181], v[56:59]
	v_mfma_f32_16x16x32_bf16 v[48:51], v[154:157], v[178:181], v[48:51]
	v_mfma_f32_16x16x32_bf16 v[40:43], v[142:145], v[186:189], v[40:43]
	v_mfma_f32_16x16x32_bf16 v[32:35], v[154:157], v[186:189], v[32:35]
	v_mfma_f32_16x16x32_bf16 v[24:27], v[142:145], v[194:197], v[24:27]
	v_mfma_f32_16x16x32_bf16 v[16:19], v[154:157], v[194:197], v[16:19]
	v_mfma_f32_16x16x32_bf16 v[8:11], v[142:145], v[216:219], v[8:11]
	v_mfma_f32_16x16x32_bf16 v[0:3], v[154:157], v[216:219], v[0:3]
	s_setprio 0
	s_setprio 1
	v_mfma_f32_16x16x32_bf16 v[60:63], v[158:161], v[174:177], v[60:63]
	v_mfma_f32_16x16x32_bf16 v[52:55], v[166:169], v[174:177], v[52:55]
	v_mfma_f32_16x16x32_bf16 v[44:47], v[158:161], v[182:185], v[44:47]
	v_mfma_f32_16x16x32_bf16 v[36:39], v[166:169], v[182:185], v[36:39]
	v_mfma_f32_16x16x32_bf16 v[28:31], v[158:161], v[190:193], v[28:31]
	v_mfma_f32_16x16x32_bf16 v[20:23], v[166:169], v[190:193], v[20:23]
	v_mfma_f32_16x16x32_bf16 v[12:15], v[158:161], v[212:215], v[12:15]
	v_mfma_f32_16x16x32_bf16 v[4:7], v[166:169], v[212:215], v[4:7]
	v_mfma_f32_16x16x32_bf16 v[60:63], v[162:165], v[178:181], v[60:63]
	v_mfma_f32_16x16x32_bf16 v[52:55], v[170:173], v[178:181], v[52:55]
	v_mfma_f32_16x16x32_bf16 v[44:47], v[162:165], v[186:189], v[44:47]
	v_mfma_f32_16x16x32_bf16 v[36:39], v[170:173], v[186:189], v[36:39]
	v_mfma_f32_16x16x32_bf16 v[28:31], v[162:165], v[194:197], v[28:31]
	v_mfma_f32_16x16x32_bf16 v[20:23], v[170:173], v[194:197], v[20:23]
	v_mfma_f32_16x16x32_bf16 v[12:15], v[162:165], v[216:219], v[12:15]
	v_mfma_f32_16x16x32_bf16 v[4:7], v[170:173], v[216:219], v[4:7]
	s_setprio 0
	s_barrier
	s_add_i32 s61, s61, 2
	s_add_u32 s30, s30, 0x100
	s_addc_u32 s31, s31, 0
	s_add_u32 s35, s35, 0x100
	s_addc_u32 s52, s52, 0
